# v9: GEMM loops VALU-free (all DMA saddr form, LDS addresses hoisted), no DMA hoist, loop heads at baseline alignment; measure 1
# speedup vs baseline: 1.0007x; 1.0007x over previous
; #define PG8_STAGE(bufoff, gbase, voff) do { _Pragma("unroll") for (int _i = 0; _i < 2; ++_i) \
;         __builtin_amdgcn_global_load_lds((const unsigned*)((const char*)(gbase) + (voff)[_i]), (LAS unsigned*)(lds + (bufoff) + ldsw + _i * 8192), 16, 0, 0); } while (0)
; #define PG8_LDA(dst, b, h) do { _Pragma("unroll") for (int m = 0; m < 4; ++m) _Pragma("unroll") for (int k = 0; k < 2; ++k) dst[m][k] = *(const LAS bf16x8*)(lds + PG8_SA(b, h) + aoff + m * 2048 + k * 1024); } while (0)
; #define PG8_LDB(dst, b, h) do { _Pragma("unroll") for (int n = 0; n < 2; ++n) _Pragma("unroll") for (int k = 0; k < 2; ++k) dst[n][k] = *(const LAS bf16x8*)(lds + PG8_SB(b, h) + boff + n * 2048 + k * 1024); } while (0)
; #define PG8_MMA(ai, bj, At, Bt) do { __builtin_amdgcn_s_setprio(1); _Pragma("unroll") for (int m = 0; m < 4; ++m) _Pragma("unroll") for (int n = 0; n < 2; ++n) _Pragma("unroll") for (int k = 0; k < 2; ++k) \
;         acc[ai][bj][m][n] = __builtin_amdgcn_mfma_f32_16x16x32_bf16(Bt[n][k], At[m][k], acc[ai][bj][m][n], 0, 0, 0); __builtin_amdgcn_s_setprio(0); } while (0)
; #define PG8_WAIT_V(n) asm volatile("s_waitcnt vmcnt(" #n ")" ::: "memory")
; #define PG8_WAIT_L(n) asm volatile("s_waitcnt lgkmcnt(" #n ")" ::: "memory")
; template <class Epi, class Ptrs>
; __device__ __forceinline__ void gemm_phase(LAS unsigned char* lds, const int K, const StaticOrder& S, const Ptrs& P, const Epi& E) {
;     ...
;         for (int t = 0; t < nt; t += 2) {
;             const bool last = (t == nt - 2);
;             const char* a1 = cA + (size_t)(t + 1) * kstep;
;             const char* a2 = last ? nA : cA + (size_t)(t + 2) * kstep; const char* b2 = last ? nB : cB + (size_t)(t + 2) * kstep;
;             const char* a3 = a2 + kstep; const char* b3 = b2 + kstep;
;             PG8_LDB(B0, 0, 0); PG8_SCHED; PG8_LDA(At, 0, 0); PG8_STAGE(PG8_SA(1, 1), a1 + hstep, voffA);
;             PG8_WAIT_L(8); PG8_BAR; PG8_WAIT_L(0); PG8_MMA(0, 0, At, B0); PG8_BAR; PG8_SCHED;
;             PG8_LDB(B1, 0, 1); PG8_STAGE(PG8_SB(0, 0), b2, voffB);
;             PG8_BAR; PG8_WAIT_L(0); PG8_MMA(0, 1, At, B1); PG8_BAR;
;             PG8_LDA(At, 0, 1); PG8_STAGE(PG8_SA(0, 0), a2, voffA);
;             PG8_BAR; PG8_WAIT_L(0); PG8_MMA(1, 0, At, B0); PG8_BAR; PG8_SCHED;
;             PG8_STAGE(PG8_SB(0, 1), b2 + hstep, voffB);
;             PG8_WAIT_V(6); PG8_BAR; PG8_MMA(1, 1, At, B1); PG8_BAR;
.LBB0_127:
	ds_read_b128 v[150:153], v205
	ds_read_b128 v[154:157], v205 offset:1024
	ds_read_b128 v[158:161], v205 offset:2048
	ds_read_b128 v[162:165], v205 offset:3072
	s_add_u32 s69, s6, 0xfffc0080
	s_addc_u32 s71, s7, -1
	s_cmp_eq_u32 s63, 12
	s_cselect_b32 s81, s1, s71
	s_cselect_b32 s80, s0, s69
	s_cselect_b32 s79, s73, s25
	s_cselect_b32 s78, s72, s20
	s_add_i32 m0, s67, 0xc000
	ds_read_b128 v[166:169], v206
	ds_read_b128 v[170:173], v206 offset:1024
	ds_read_b128 v[174:177], v206 offset:2048
	ds_read_b128 v[178:181], v206 offset:3072
	ds_read_b128 v[182:185], v206 offset:4096
	ds_read_b128 v[186:189], v206 offset:5120
	ds_read_b128 v[190:193], v206 offset:6144
	ds_read_b128 v[194:197], v206 offset:7168
	global_load_lds_dwordx4 v142, s[6:7]
	s_add_i32 m0, s67, 0xe000
	s_nop 0
	global_load_lds_dwordx4 v144, s[6:7]
	s_waitcnt lgkmcnt(8)
	s_barrier
	s_waitcnt lgkmcnt(0)
	s_setprio 1
	s_waitcnt lgkmcnt(0)
	v_mfma_f32_16x16x32_bf16 v[120:123], v[150:153], v[166:169], v[120:123]
	v_mfma_f32_16x16x32_bf16 v[120:123], v[154:157], v[170:173], v[120:123]
	v_mfma_f32_16x16x32_bf16 v[116:119], v[162:165], v[170:173], v[116:119]
	v_mfma_f32_16x16x32_bf16 v[116:119], v[158:161], v[166:169], v[116:119]
	v_mfma_f32_16x16x32_bf16 v[100:103], v[158:161], v[174:177], v[100:103]
	v_mfma_f32_16x16x32_bf16 v[100:103], v[162:165], v[178:181], v[100:103]
	v_mfma_f32_16x16x32_bf16 v[104:107], v[154:157], v[178:181], v[104:107]
	v_mfma_f32_16x16x32_bf16 v[104:107], v[150:153], v[174:177], v[104:107]
	v_mfma_f32_16x16x32_bf16 v[88:91], v[150:153], v[182:185], v[88:91]
	v_mfma_f32_16x16x32_bf16 v[88:91], v[154:157], v[186:189], v[88:91]
	v_mfma_f32_16x16x32_bf16 v[84:87], v[162:165], v[186:189], v[84:87]
	v_mfma_f32_16x16x32_bf16 v[84:87], v[158:161], v[182:185], v[84:87]
	v_mfma_f32_16x16x32_bf16 v[68:71], v[158:161], v[190:193], v[68:71]
	v_mfma_f32_16x16x32_bf16 v[68:71], v[162:165], v[194:197], v[68:71]
	v_mfma_f32_16x16x32_bf16 v[72:75], v[154:157], v[194:197], v[72:75]
	v_mfma_f32_16x16x32_bf16 v[72:75], v[150:153], v[190:193], v[72:75]
	s_setprio 0
	s_barrier
	s_add_i32 s69, s91, s65
	s_add_u32 s100, s78, 0x80
	s_addc_u32 s101, s79, 0
	s_mov_b32 m0, s69
	ds_read_b128 v[198:201], v207
	ds_read_b128 v[210:213], v207 offset:1024
	ds_read_b128 v[214:217], v207 offset:2048
	ds_read_b128 v[218:221], v207 offset:3072
	global_load_lds_dwordx4 v134, s[78:79]
	s_add_i32 m0, s69, 0x2000
	s_nop 0
	global_load_lds_dwordx4 v138, s[78:79]
	s_barrier
	s_waitcnt lgkmcnt(0)
	s_setprio 1
	s_waitcnt lgkmcnt(0)
	v_mfma_f32_16x16x32_bf16 v[124:127], v[198:201], v[166:169], v[124:127]
	v_mfma_f32_16x16x32_bf16 v[124:127], v[210:213], v[170:173], v[124:127]
	v_mfma_f32_16x16x32_bf16 v[112:115], v[218:221], v[170:173], v[112:115]
	v_mfma_f32_16x16x32_bf16 v[112:115], v[214:217], v[166:169], v[112:115]
	v_mfma_f32_16x16x32_bf16 v[96:99], v[214:217], v[174:177], v[96:99]
	v_mfma_f32_16x16x32_bf16 v[96:99], v[218:221], v[178:181], v[96:99]
	v_mfma_f32_16x16x32_bf16 v[108:111], v[210:213], v[178:181], v[108:111]
	v_mfma_f32_16x16x32_bf16 v[108:111], v[198:201], v[174:177], v[108:111]
	v_mfma_f32_16x16x32_bf16 v[92:95], v[198:201], v[182:185], v[92:95]
	v_mfma_f32_16x16x32_bf16 v[92:95], v[210:213], v[186:189], v[92:95]
	v_mfma_f32_16x16x32_bf16 v[80:83], v[218:221], v[186:189], v[80:83]
	v_mfma_f32_16x16x32_bf16 v[80:83], v[214:217], v[182:185], v[80:83]
	v_mfma_f32_16x16x32_bf16 v[64:67], v[214:217], v[190:193], v[64:67]
	v_mfma_f32_16x16x32_bf16 v[64:67], v[218:221], v[194:197], v[64:67]
	v_mfma_f32_16x16x32_bf16 v[76:79], v[210:213], v[194:197], v[76:79]
	v_mfma_f32_16x16x32_bf16 v[76:79], v[198:201], v[190:193], v[76:79]
	s_setprio 0
	s_mov_b32 m0, s67
	s_barrier
	ds_read_b128 v[166:169], v206 offset:16384
	ds_read_b128 v[170:173], v206 offset:17408
	ds_read_b128 v[174:177], v206 offset:18432
	ds_read_b128 v[178:181], v206 offset:19456
	ds_read_b128 v[182:185], v206 offset:20480
	ds_read_b128 v[186:189], v206 offset:21504
	ds_read_b128 v[190:193], v206 offset:22528
	ds_read_b128 v[194:197], v206 offset:23552
	global_load_lds_dwordx4 v132, s[80:81]
	s_mov_b32 m0, s75
	s_nop 0
	global_load_lds_dwordx4 v136, s[80:81]
	s_barrier
	s_waitcnt lgkmcnt(0)
	s_setprio 1
	s_waitcnt lgkmcnt(0)
	v_mfma_f32_16x16x32_bf16 v[56:59], v[150:153], v[166:169], v[56:59]
	v_mfma_f32_16x16x32_bf16 v[56:59], v[154:157], v[170:173], v[56:59]
	v_mfma_f32_16x16x32_bf16 v[52:55], v[162:165], v[170:173], v[52:55]
	v_mfma_f32_16x16x32_bf16 v[52:55], v[158:161], v[166:169], v[52:55]
	v_mfma_f32_16x16x32_bf16 v[36:39], v[158:161], v[174:177], v[36:39]
	v_mfma_f32_16x16x32_bf16 v[36:39], v[162:165], v[178:181], v[36:39]
	v_mfma_f32_16x16x32_bf16 v[40:43], v[154:157], v[178:181], v[40:43]
	v_mfma_f32_16x16x32_bf16 v[40:43], v[150:153], v[174:177], v[40:43]
	v_mfma_f32_16x16x32_bf16 v[24:27], v[150:153], v[182:185], v[24:27]
	v_mfma_f32_16x16x32_bf16 v[24:27], v[154:157], v[186:189], v[24:27]
	v_mfma_f32_16x16x32_bf16 v[20:23], v[162:165], v[186:189], v[20:23]
	v_mfma_f32_16x16x32_bf16 v[20:23], v[158:161], v[182:185], v[20:23]
	v_mfma_f32_16x16x32_bf16 v[4:7], v[158:161], v[190:193], v[4:7]
	v_mfma_f32_16x16x32_bf16 v[4:7], v[162:165], v[194:197], v[4:7]
	v_mfma_f32_16x16x32_bf16 v[8:11], v[154:157], v[194:197], v[8:11]
	v_mfma_f32_16x16x32_bf16 v[8:11], v[150:153], v[190:193], v[8:11]
	s_setprio 0
	s_barrier
	s_add_u32 s82, s78, 0x40000
	s_addc_u32 s83, s79, 0
	s_add_i32 s69, s92, s65
	s_mov_b32 m0, s69
	s_nop 0
	global_load_lds_dwordx4 v134, s[82:83]
	s_add_i32 m0, s69, 0x2000
	s_nop 0
	global_load_lds_dwordx4 v138, s[82:83]
	s_waitcnt vmcnt(6)
	s_barrier
; #define PG8_STAGE(bufoff, gbase, voff) do { _Pragma("unroll") for (int _i = 0; _i < 2; ++_i) \
;         __builtin_amdgcn_global_load_lds((const unsigned*)((const char*)(gbase) + (voff)[_i]), (LAS unsigned*)(lds + (bufoff) + ldsw + _i * 8192), 16, 0, 0); } while (0)
; #define PG8_LDA(dst, b, h) do { _Pragma("unroll") for (int m = 0; m < 4; ++m) _Pragma("unroll") for (int k = 0; k < 2; ++k) dst[m][k] = *(const LAS bf16x8*)(lds + PG8_SA(b, h) + aoff + m * 2048 + k * 1024); } while (0)
; #define PG8_LDB(dst, b, h) do { _Pragma("unroll") for (int n = 0; n < 2; ++n) _Pragma("unroll") for (int k = 0; k < 2; ++k) dst[n][k] = *(const LAS bf16x8*)(lds + PG8_SB(b, h) + boff + n * 2048 + k * 1024); } while (0)
; #define PG8_MMA(ai, bj, At, Bt) do { __builtin_amdgcn_s_setprio(1); _Pragma("unroll") for (int m = 0; m < 4; ++m) _Pragma("unroll") for (int n = 0; n < 2; ++n) _Pragma("unroll") for (int k = 0; k < 2; ++k) \
;         acc[ai][bj][m][n] = __builtin_amdgcn_mfma_f32_16x16x32_bf16(Bt[n][k], At[m][k], acc[ai][bj][m][n], 0, 0, 0); __builtin_amdgcn_s_setprio(0); } while (0)
; #define PG8_WAIT_V(n) asm volatile("s_waitcnt vmcnt(" #n ")" ::: "memory")
; #define PG8_WAIT_L(n) asm volatile("s_waitcnt lgkmcnt(" #n ")" ::: "memory")
; #define PG8_BAR __builtin_amdgcn_s_barrier()
; #define PG8_SCHED __builtin_amdgcn_sched_barrier(0)
; template <class Epi, class Ptrs>
; __device__ __forceinline__ void gemm_phase(LAS unsigned char* lds, const int K, const StaticOrder& S, const Ptrs& P, const Epi& E) {
;     ...
;             PG8_WAIT_V(6); PG8_BAR; PG8_MMA(1, 1, At, B1); PG8_BAR;
;             PG8_LDB(B0, 1, 0); PG8_SCHED; PG8_LDA(At, 1, 0); PG8_STAGE(PG8_SA(0, 1), a2 + hstep, voffA);
;             PG8_WAIT_L(8); PG8_BAR; PG8_WAIT_L(0); PG8_MMA(0, 0, At, B0); PG8_BAR; PG8_SCHED;
;             PG8_LDB(B1, 1, 1); PG8_STAGE(PG8_SB(1, 0), b3, voffB);
;             PG8_BAR; PG8_WAIT_L(0); PG8_MMA(0, 1, At, B1); PG8_BAR;
;             PG8_LDA(At, 1, 1); PG8_STAGE(PG8_SA(1, 0), a3, voffA);
;             PG8_BAR; PG8_WAIT_L(0); PG8_MMA(1, 0, At, B0); PG8_BAR; PG8_SCHED;
	s_setprio 1
	v_mfma_f32_16x16x32_bf16 v[60:63], v[198:201], v[166:169], v[60:63]
	v_mfma_f32_16x16x32_bf16 v[60:63], v[210:213], v[170:173], v[60:63]
	v_mfma_f32_16x16x32_bf16 v[48:51], v[218:221], v[170:173], v[48:51]
	v_mfma_f32_16x16x32_bf16 v[48:51], v[214:217], v[166:169], v[48:51]
	v_mfma_f32_16x16x32_bf16 v[32:35], v[214:217], v[174:177], v[32:35]
	v_mfma_f32_16x16x32_bf16 v[32:35], v[218:221], v[178:181], v[32:35]
	v_mfma_f32_16x16x32_bf16 v[44:47], v[210:213], v[178:181], v[44:47]
	v_mfma_f32_16x16x32_bf16 v[44:47], v[198:201], v[174:177], v[44:47]
	v_mfma_f32_16x16x32_bf16 v[28:31], v[198:201], v[182:185], v[28:31]
	v_mfma_f32_16x16x32_bf16 v[28:31], v[210:213], v[186:189], v[28:31]
	v_mfma_f32_16x16x32_bf16 v[16:19], v[218:221], v[186:189], v[16:19]
	v_mfma_f32_16x16x32_bf16 v[16:19], v[214:217], v[182:185], v[16:19]
	v_mfma_f32_16x16x32_bf16 v[0:3], v[214:217], v[190:193], v[0:3]
	v_mfma_f32_16x16x32_bf16 v[0:3], v[218:221], v[194:197], v[0:3]
	v_mfma_f32_16x16x32_bf16 v[12:15], v[210:213], v[194:197], v[12:15]
	v_mfma_f32_16x16x32_bf16 v[12:15], v[198:201], v[190:193], v[12:15]
	s_setprio 0
	s_add_i32 s69, 0, 0x18000
	s_barrier
	ds_read_b128 v[150:153], v252
	ds_read_b128 v[154:157], v252 offset:1024
	ds_read_b128 v[158:161], v252 offset:2048
	ds_read_b128 v[162:165], v252 offset:3072
	s_add_u32 s80, s80, 0x40000
	s_addc_u32 s81, s81, 0
	s_mov_b32 m0, s77
	ds_read_b128 v[166:169], v206 offset:32768
	ds_read_b128 v[170:173], v206 offset:33792
	ds_read_b128 v[174:177], v206 offset:34816
	ds_read_b128 v[178:181], v206 offset:35840
	ds_read_b128 v[182:185], v206 offset:36864
	ds_read_b128 v[186:189], v206 offset:37888
	ds_read_b128 v[190:193], v206 offset:38912
	ds_read_b128 v[194:197], v206 offset:39936
	global_load_lds_dwordx4 v132, s[80:81]
	s_mov_b32 m0, s85
	s_nop 0
	global_load_lds_dwordx4 v136, s[80:81]
	s_waitcnt lgkmcnt(8)
	s_barrier
	s_waitcnt lgkmcnt(0)
	s_setprio 1
	s_waitcnt lgkmcnt(0)
	v_mfma_f32_16x16x32_bf16 v[120:123], v[150:153], v[166:169], v[120:123]
	v_mfma_f32_16x16x32_bf16 v[120:123], v[154:157], v[170:173], v[120:123]
	v_mfma_f32_16x16x32_bf16 v[116:119], v[162:165], v[170:173], v[116:119]
	v_mfma_f32_16x16x32_bf16 v[116:119], v[158:161], v[166:169], v[116:119]
	v_mfma_f32_16x16x32_bf16 v[100:103], v[158:161], v[174:177], v[100:103]
	v_mfma_f32_16x16x32_bf16 v[100:103], v[162:165], v[178:181], v[100:103]
	v_mfma_f32_16x16x32_bf16 v[104:107], v[154:157], v[178:181], v[104:107]
	v_mfma_f32_16x16x32_bf16 v[104:107], v[150:153], v[174:177], v[104:107]
	v_mfma_f32_16x16x32_bf16 v[88:91], v[150:153], v[182:185], v[88:91]
	v_mfma_f32_16x16x32_bf16 v[88:91], v[154:157], v[186:189], v[88:91]
	v_mfma_f32_16x16x32_bf16 v[84:87], v[162:165], v[186:189], v[84:87]
	v_mfma_f32_16x16x32_bf16 v[84:87], v[158:161], v[182:185], v[84:87]
	v_mfma_f32_16x16x32_bf16 v[68:71], v[158:161], v[190:193], v[68:71]
	v_mfma_f32_16x16x32_bf16 v[68:71], v[162:165], v[194:197], v[68:71]
	v_mfma_f32_16x16x32_bf16 v[72:75], v[154:157], v[194:197], v[72:75]
	v_mfma_f32_16x16x32_bf16 v[72:75], v[150:153], v[190:193], v[72:75]
	s_setprio 0
	s_barrier
	s_add_i32 s71, 0, 0x1c000
	s_add_i32 s69, s69, s65
	s_mov_b32 m0, s69
	ds_read_b128 v[198:201], v253
	ds_read_b128 v[210:213], v253 offset:1024
	ds_read_b128 v[214:217], v253 offset:2048
	ds_read_b128 v[218:221], v253 offset:3072
	global_load_lds_dwordx4 v134, s[100:101]
	s_add_i32 m0, s69, 0x2000
	s_nop 0
	global_load_lds_dwordx4 v138, s[100:101]
	s_barrier
	s_waitcnt lgkmcnt(0)
	s_setprio 1
	s_waitcnt lgkmcnt(0)
	v_mfma_f32_16x16x32_bf16 v[124:127], v[198:201], v[166:169], v[124:127]
	v_mfma_f32_16x16x32_bf16 v[124:127], v[210:213], v[170:173], v[124:127]
	v_mfma_f32_16x16x32_bf16 v[112:115], v[218:221], v[170:173], v[112:115]
	v_mfma_f32_16x16x32_bf16 v[112:115], v[214:217], v[166:169], v[112:115]
	v_mfma_f32_16x16x32_bf16 v[96:99], v[214:217], v[174:177], v[96:99]
	v_mfma_f32_16x16x32_bf16 v[96:99], v[218:221], v[178:181], v[96:99]
	v_mfma_f32_16x16x32_bf16 v[108:111], v[210:213], v[178:181], v[108:111]
	v_mfma_f32_16x16x32_bf16 v[108:111], v[198:201], v[174:177], v[108:111]
	v_mfma_f32_16x16x32_bf16 v[92:95], v[198:201], v[182:185], v[92:95]
	v_mfma_f32_16x16x32_bf16 v[92:95], v[210:213], v[186:189], v[92:95]
	v_mfma_f32_16x16x32_bf16 v[80:83], v[218:221], v[186:189], v[80:83]
	v_mfma_f32_16x16x32_bf16 v[80:83], v[214:217], v[182:185], v[80:83]
	v_mfma_f32_16x16x32_bf16 v[64:67], v[214:217], v[190:193], v[64:67]
	v_mfma_f32_16x16x32_bf16 v[64:67], v[218:221], v[194:197], v[64:67]
	v_mfma_f32_16x16x32_bf16 v[76:79], v[210:213], v[194:197], v[76:79]
	v_mfma_f32_16x16x32_bf16 v[76:79], v[198:201], v[190:193], v[76:79]
	s_setprio 0
	s_mov_b32 m0, s89
	s_add_u32 s100, s80, 0xfffc0080
	s_addc_u32 s101, s81, -1
	s_barrier
; template <class Epi, class Ptrs>
; __device__ __forceinline__ void gemm_phase(LAS unsigned char* lds, const int K, const StaticOrder& S, const Ptrs& P, const Epi& E) {
;     ...
;             PG8_LDA(At, 1, 1); PG8_STAGE(PG8_SA(1, 0), a3, voffA);
;             PG8_BAR; PG8_WAIT_L(0); PG8_MMA(1, 0, At, B0); PG8_BAR; PG8_SCHED;
;             PG8_STAGE(PG8_SB(1, 1), b3 + hstep, voffB);
;             PG8_WAIT_V(6); PG8_BAR; PG8_MMA(1, 1, At, B1); PG8_BAR;
;         }
;     __device__ __forceinline__ void operator()(const f32x4 (&acc)[2][2][4][2], const Unit& u, int ui, int wr, int wc, int fr, int fq) const {
;         const int pn = u.pn;
;         if (pn < 8) {
;             bf16_t* base = (bf16_t*)(ws + WS_U) + (size_t)(u.pm * 256 + wr * 64 + fr) * DM + pn * 128 + wc * 32 + 8 * fq;
; #pragma unroll
;             for (int ai = 0; ai < 2; ++ai)
; #pragma unroll
;                 for (int m = 0; m < 4; ++m) {
;                     const f32x4 g0 = g1_4(acc[ai][0][m][0], acc[ai][1][m][0]), g1 = g1_4(acc[ai][0][m][1], acc[ai][1][m][1]);
;                     *(u32x4*)(base + (size_t)(ai * 128 + m * 16) * DM) = pack8(g0, g1); }
;             return; }
;         if (pn >= 17 && pn < 21) {
;             bf16_t* base = (bf16_t*)(dout + DO_GVT) + (size_t)((pn - 17) * 256 + wr * 64 + fr) * MTOK + u.pm * 256 + wc * 32 + 8 * fq;
;             float* pp = (float*)(ws + WS_PART) + (size_t)(u.pm * 256 + wc * 32 + 8 * fq) * 8 + (pn - 17) * 2 + wr;
; #pragma unroll
;             for (int bj = 0; bj < 2; ++bj) { f32x4 sq0 = {0.f, 0.f, 0.f, 0.f}, sq1 = {0.f, 0.f, 0.f, 0.f};
; #pragma unroll
;                 for (int ai = 0; ai < 2; ++ai)
; #pragma unroll
;                     for (int m = 0; m < 4; ++m) { const f32x4 g0 = gelu4(acc[ai][bj][m][0]), g1 = gelu4(acc[ai][bj][m][1]);
;                         sq0 += g0 * g0; sq1 += g1 * g1;
;                         *(u32x4*)(base + (size_t)(ai * 128 + m * 16) * MTOK + bj * 128) = pack8(g0, g1); }
; #pragma unroll
;                 for (int j = 0; j < 4; ++j) { const float t0 = row16_sum(sq0[j]), t1 = row16_sum(sq1[j]); if (fr == 0) { pp[(size_t)(bj * 128 + j) * 8] = t0; pp[(size_t)(bj * 128 + 4 + j) * 8] = t1; } } }
;             return; }
;         bf16_t* base; size_t ld; int row0, col0, act;
;         if (pn < 12)      { base = (bf16_t*)(ws + WS_Q);  ld = DM;  row0 = u.pm * 256; col0 = (pn - 8) * 256;  act = 0; }
	ds_read_b128 v[166:169], v206 offset:49152
	ds_read_b128 v[170:173], v206 offset:50176
	ds_read_b128 v[174:177], v206 offset:51200
	ds_read_b128 v[178:181], v206 offset:52224
	ds_read_b128 v[182:185], v206 offset:53248
	ds_read_b128 v[186:189], v206 offset:54272
	ds_read_b128 v[190:193], v206 offset:55296
	ds_read_b128 v[194:197], v206 offset:56320
	global_load_lds_dwordx4 v132, s[100:101]
	s_mov_b32 m0, s90
	s_nop 0
	global_load_lds_dwordx4 v136, s[100:101]
	s_barrier
	s_waitcnt lgkmcnt(0)
	s_setprio 1
	s_waitcnt lgkmcnt(0)
	v_mfma_f32_16x16x32_bf16 v[56:59], v[150:153], v[166:169], v[56:59]
	v_mfma_f32_16x16x32_bf16 v[56:59], v[154:157], v[170:173], v[56:59]
	v_mfma_f32_16x16x32_bf16 v[52:55], v[162:165], v[170:173], v[52:55]
	v_mfma_f32_16x16x32_bf16 v[52:55], v[158:161], v[166:169], v[52:55]
	v_mfma_f32_16x16x32_bf16 v[36:39], v[158:161], v[174:177], v[36:39]
	v_mfma_f32_16x16x32_bf16 v[36:39], v[162:165], v[178:181], v[36:39]
	v_mfma_f32_16x16x32_bf16 v[40:43], v[154:157], v[178:181], v[40:43]
	v_mfma_f32_16x16x32_bf16 v[40:43], v[150:153], v[174:177], v[40:43]
	v_mfma_f32_16x16x32_bf16 v[24:27], v[150:153], v[182:185], v[24:27]
	v_mfma_f32_16x16x32_bf16 v[24:27], v[154:157], v[186:189], v[24:27]
	v_mfma_f32_16x16x32_bf16 v[20:23], v[162:165], v[186:189], v[20:23]
	v_mfma_f32_16x16x32_bf16 v[20:23], v[158:161], v[182:185], v[20:23]
	v_mfma_f32_16x16x32_bf16 v[4:7], v[158:161], v[190:193], v[4:7]
	v_mfma_f32_16x16x32_bf16 v[4:7], v[162:165], v[194:197], v[4:7]
	v_mfma_f32_16x16x32_bf16 v[8:11], v[154:157], v[194:197], v[8:11]
	v_mfma_f32_16x16x32_bf16 v[8:11], v[150:153], v[190:193], v[8:11]
	s_setprio 0
	s_barrier
	s_add_u32 s78, s78, 0x40080
	s_addc_u32 s79, s79, 0
	s_add_i32 s69, s71, s65
	s_mov_b32 m0, s69
	s_nop 0
	global_load_lds_dwordx4 v134, s[78:79]
	s_add_i32 m0, s69, 0x2000
	s_nop 0
	global_load_lds_dwordx4 v138, s[78:79]
	s_waitcnt vmcnt(6)
	s_barrier
	s_setprio 1
	v_mfma_f32_16x16x32_bf16 v[60:63], v[198:201], v[166:169], v[60:63]
	v_mfma_f32_16x16x32_bf16 v[60:63], v[210:213], v[170:173], v[60:63]
	v_mfma_f32_16x16x32_bf16 v[48:51], v[218:221], v[170:173], v[48:51]
	v_mfma_f32_16x16x32_bf16 v[48:51], v[214:217], v[166:169], v[48:51]
	v_mfma_f32_16x16x32_bf16 v[32:35], v[214:217], v[174:177], v[32:35]
	v_mfma_f32_16x16x32_bf16 v[32:35], v[218:221], v[178:181], v[32:35]
	v_mfma_f32_16x16x32_bf16 v[44:47], v[210:213], v[178:181], v[44:47]
	v_mfma_f32_16x16x32_bf16 v[44:47], v[198:201], v[174:177], v[44:47]
	v_mfma_f32_16x16x32_bf16 v[28:31], v[198:201], v[182:185], v[28:31]
	v_mfma_f32_16x16x32_bf16 v[28:31], v[210:213], v[186:189], v[28:31]
	v_mfma_f32_16x16x32_bf16 v[16:19], v[218:221], v[186:189], v[16:19]
	v_mfma_f32_16x16x32_bf16 v[16:19], v[214:217], v[182:185], v[16:19]
	v_mfma_f32_16x16x32_bf16 v[0:3], v[214:217], v[190:193], v[0:3]
	v_mfma_f32_16x16x32_bf16 v[0:3], v[218:221], v[194:197], v[0:3]
	v_mfma_f32_16x16x32_bf16 v[12:15], v[210:213], v[194:197], v[12:15]
	v_mfma_f32_16x16x32_bf16 v[12:15], v[198:201], v[190:193], v[12:15]
	s_setprio 0
	s_add_i32 s63, s63, 2
	s_add_u32 s6, s6, 0x100
	s_addc_u32 s7, s7, 0
	s_add_u32 s20, s20, 0x100
	s_addc_u32 s25, s25, 0
	s_cmp_gt_u32 s63, 13
	s_barrier
	s_cbranch_scc0 .LBB0_127
	s_nop 0
	s_nop 0
	s_nop 0
	s_nop 0
	s_nop 0
	s_nop 0
	s_nop 0
	s_nop 0
	s_nop 0
	s_nop 0
	s_nop 0
	s_nop 0
	s_nop 0
	s_nop 0
	s_nop 0
	s_nop 0
	s_nop 0
	s_nop 0
	s_nop 0
	s_nop 0
	s_nop 0
	s_nop 0
	s_nop 0
	s_nop 0
	s_nop 0
	s_nop 0
	s_nop 0
	s_nop 0
	s_cmp_gt_i32 s74, 7
	s_mov_b64 s[6:7], -1
	s_cbranch_scc0 .LBB0_188
	s_sub_i32 s25, s74, 17
	s_cmp_gt_u32 s25, 3
	s_cbranch_scc0 .LBB0_170
	s_lshl_b32 s69, s76, 8
	s_cmp_gt_u32 s74, 11
	s_cbranch_scc0 .LBB0_135
	s_cmp_eq_u32 s74, 12
	s_mov_b64 s[6:7], 0
	s_cbranch_scc1 .LBB0_134
	s_cmp_gt_u32 s74, 16
	s_cbranch_scc1 .LBB0_191
	s_lshl_b32 s20, s74, 8
	v_readlane_b32 s80, v254, 2
	s_addk_i32 s20, 0xf300
	s_mov_b64 s[78:79], 0x400
	s_mov_b64 s[82:83], -1
	s_mov_b32 s63, s69
	v_readlane_b32 s81, v254, 3
	s_andn2_b64 vcc, exec, s[6:7]
	s_cbranch_vccz .LBB0_136
	s_branch .LBB0_137

; #define PG8_STAGE(bufoff, gbase, voff) do { _Pragma("unroll") for (int _i = 0; _i < 2; ++_i) \
;         __builtin_amdgcn_global_load_lds((const unsigned*)((const char*)(gbase) + (voff)[_i]), (LAS unsigned*)(lds + (bufoff) + ldsw + _i * 8192), 16, 0, 0); } while (0)
; #define PG8_LDA(dst, b, h) do { _Pragma("unroll") for (int m = 0; m < 4; ++m) _Pragma("unroll") for (int k = 0; k < 2; ++k) dst[m][k] = *(const LAS bf16x8*)(lds + PG8_SA(b, h) + aoff + m * 2048 + k * 1024); } while (0)
; #define PG8_LDB(dst, b, h) do { _Pragma("unroll") for (int n = 0; n < 2; ++n) _Pragma("unroll") for (int k = 0; k < 2; ++k) dst[n][k] = *(const LAS bf16x8*)(lds + PG8_SB(b, h) + boff + n * 2048 + k * 1024); } while (0)
; #define PG8_MMA(ai, bj, At, Bt) do { __builtin_amdgcn_s_setprio(1); _Pragma("unroll") for (int m = 0; m < 4; ++m) _Pragma("unroll") for (int n = 0; n < 2; ++n) _Pragma("unroll") for (int k = 0; k < 2; ++k) \
;         acc[ai][bj][m][n] = __builtin_amdgcn_mfma_f32_16x16x32_bf16(Bt[n][k], At[m][k], acc[ai][bj][m][n], 0, 0, 0); __builtin_amdgcn_s_setprio(0); } while (0)
; #define PG8_WAIT_V(n) asm volatile("s_waitcnt vmcnt(" #n ")" ::: "memory")
; #define PG8_WAIT_L(n) asm volatile("s_waitcnt lgkmcnt(" #n ")" ::: "memory")
; template <class Epi, class Ptrs>
; __device__ __forceinline__ void gemm_phase(LAS unsigned char* lds, const int K, const StaticOrder& S, const Ptrs& P, const Epi& E) {
;     ...
;         for (int t = 0; t < nt; t += 2) {
;             const bool last = (t == nt - 2);
;             const char* a1 = cA + (size_t)(t + 1) * kstep;
;             const char* a2 = last ? nA : cA + (size_t)(t + 2) * kstep; const char* b2 = last ? nB : cB + (size_t)(t + 2) * kstep;
;             const char* a3 = a2 + kstep; const char* b3 = b2 + kstep;
;             PG8_LDB(B0, 0, 0); PG8_SCHED; PG8_LDA(At, 0, 0); PG8_STAGE(PG8_SA(1, 1), a1 + hstep, voffA);
;             PG8_WAIT_L(8); PG8_BAR; PG8_WAIT_L(0); PG8_MMA(0, 0, At, B0); PG8_BAR; PG8_SCHED;
;             PG8_LDB(B1, 0, 1); PG8_STAGE(PG8_SB(0, 0), b2, voffB);
;             PG8_BAR; PG8_WAIT_L(0); PG8_MMA(0, 1, At, B1); PG8_BAR;
;             PG8_LDA(At, 0, 1); PG8_STAGE(PG8_SA(0, 0), a2, voffA);
;             PG8_BAR; PG8_WAIT_L(0); PG8_MMA(1, 0, At, B0); PG8_BAR; PG8_SCHED;
;             PG8_STAGE(PG8_SB(0, 1), b2 + hstep, voffB);
;             PG8_WAIT_V(6); PG8_BAR; PG8_MMA(1, 1, At, B1); PG8_BAR;
.LBB0_353:
	ds_read_b128 v[128:131], v207
	ds_read_b128 v[132:135], v207 offset:1024
	ds_read_b128 v[136:139], v207 offset:2048
	ds_read_b128 v[140:143], v207 offset:3072
	s_add_u32 s42, s38, 0xfffc0080
	s_addc_u32 s43, s39, -1
	s_cmp_eq_u32 s41, 12
	s_cselect_b32 s45, s1, s43
	s_cselect_b32 s44, s0, s42
	s_cselect_b32 s43, s25, s23
	s_cselect_b32 s42, s24, s21
	s_add_i32 m0, s54, 0xc000
	ds_read_b128 v[144:147], v209
	ds_read_b128 v[148:151], v209 offset:1024
	ds_read_b128 v[152:155], v209 offset:2048
	ds_read_b128 v[156:159], v209 offset:3072
	ds_read_b128 v[160:163], v209 offset:4096
	ds_read_b128 v[164:167], v209 offset:5120
	ds_read_b128 v[168:171], v209 offset:6144
	ds_read_b128 v[172:175], v209 offset:7168
	global_load_lds_dwordx4 v184, s[38:39]
	s_add_i32 m0, s54, 0xe000
	s_nop 0
	global_load_lds_dwordx4 v186, s[38:39]
	s_waitcnt lgkmcnt(8)
	s_barrier
	s_waitcnt lgkmcnt(0)
	s_setprio 1
	s_waitcnt lgkmcnt(0)
	v_mfma_f32_16x16x32_bf16 v[124:127], v[128:131], v[144:147], v[124:127]
	v_mfma_f32_16x16x32_bf16 v[124:127], v[132:135], v[148:151], v[124:127]
	v_mfma_f32_16x16x32_bf16 v[120:123], v[140:143], v[148:151], v[120:123]
	v_mfma_f32_16x16x32_bf16 v[120:123], v[136:139], v[144:147], v[120:123]
	v_mfma_f32_16x16x32_bf16 v[104:107], v[136:139], v[152:155], v[104:107]
	v_mfma_f32_16x16x32_bf16 v[104:107], v[140:143], v[156:159], v[104:107]
	v_mfma_f32_16x16x32_bf16 v[108:111], v[132:135], v[156:159], v[108:111]
	v_mfma_f32_16x16x32_bf16 v[108:111], v[128:131], v[152:155], v[108:111]
	v_mfma_f32_16x16x32_bf16 v[92:95], v[128:131], v[160:163], v[92:95]
	v_mfma_f32_16x16x32_bf16 v[92:95], v[132:135], v[164:167], v[92:95]
	v_mfma_f32_16x16x32_bf16 v[88:91], v[140:143], v[164:167], v[88:91]
	v_mfma_f32_16x16x32_bf16 v[88:91], v[136:139], v[160:163], v[88:91]
	v_mfma_f32_16x16x32_bf16 v[72:75], v[136:139], v[168:171], v[72:75]
	v_mfma_f32_16x16x32_bf16 v[72:75], v[140:143], v[172:175], v[72:75]
	v_mfma_f32_16x16x32_bf16 v[76:79], v[132:135], v[172:175], v[76:79]
	v_mfma_f32_16x16x32_bf16 v[76:79], v[128:131], v[168:171], v[76:79]
	s_setprio 0
	s_barrier
	s_add_i32 s69, s66, s51
	s_add_u32 s90, s42, 0x80
	s_addc_u32 s91, s43, 0
	s_mov_b32 m0, s69
	ds_read_b128 v[192:195], v210
	ds_read_b128 v[196:199], v210 offset:1024
	ds_read_b128 v[200:203], v210 offset:2048
	ds_read_b128 v[212:215], v210 offset:3072
	global_load_lds_dwordx4 v178, s[42:43]
	s_add_i32 m0, s69, 0x2000
	s_nop 0
	global_load_lds_dwordx4 v182, s[42:43]
	s_barrier
	s_waitcnt lgkmcnt(0)
	s_setprio 1
	s_waitcnt lgkmcnt(0)
	v_mfma_f32_16x16x32_bf16 v[116:119], v[192:195], v[144:147], v[116:119]
	v_mfma_f32_16x16x32_bf16 v[116:119], v[196:199], v[148:151], v[116:119]
	v_mfma_f32_16x16x32_bf16 v[112:115], v[212:215], v[148:151], v[112:115]
	v_mfma_f32_16x16x32_bf16 v[112:115], v[200:203], v[144:147], v[112:115]
	v_mfma_f32_16x16x32_bf16 v[96:99], v[200:203], v[152:155], v[96:99]
	v_mfma_f32_16x16x32_bf16 v[96:99], v[212:215], v[156:159], v[96:99]
	v_mfma_f32_16x16x32_bf16 v[100:103], v[196:199], v[156:159], v[100:103]
	v_mfma_f32_16x16x32_bf16 v[100:103], v[192:195], v[152:155], v[100:103]
	v_mfma_f32_16x16x32_bf16 v[84:87], v[192:195], v[160:163], v[84:87]
	v_mfma_f32_16x16x32_bf16 v[84:87], v[196:199], v[164:167], v[84:87]
	v_mfma_f32_16x16x32_bf16 v[80:83], v[212:215], v[164:167], v[80:83]
	v_mfma_f32_16x16x32_bf16 v[80:83], v[200:203], v[160:163], v[80:83]
	v_mfma_f32_16x16x32_bf16 v[64:67], v[200:203], v[168:171], v[64:67]
	v_mfma_f32_16x16x32_bf16 v[64:67], v[212:215], v[172:175], v[64:67]
	v_mfma_f32_16x16x32_bf16 v[68:71], v[196:199], v[172:175], v[68:71]
	v_mfma_f32_16x16x32_bf16 v[68:71], v[192:195], v[168:171], v[68:71]
	s_setprio 0
	s_mov_b32 m0, s54
	s_add_u32 s92, s44, 0x80
	s_addc_u32 s93, s45, 0
	s_barrier
	ds_read_b128 v[144:147], v209 offset:16384
	ds_read_b128 v[148:151], v209 offset:17408
	ds_read_b128 v[152:155], v209 offset:18432
	ds_read_b128 v[156:159], v209 offset:19456
	ds_read_b128 v[160:163], v209 offset:20480
	ds_read_b128 v[164:167], v209 offset:21504
	ds_read_b128 v[168:171], v209 offset:22528
	ds_read_b128 v[172:175], v209 offset:23552
	global_load_lds_dwordx4 v176, s[44:45]
	s_mov_b32 m0, s55
	s_nop 0
	global_load_lds_dwordx4 v180, s[44:45]
	s_barrier
	s_waitcnt lgkmcnt(0)
	s_setprio 1
	s_waitcnt lgkmcnt(0)
	v_mfma_f32_16x16x32_bf16 v[60:63], v[128:131], v[144:147], v[60:63]
	v_mfma_f32_16x16x32_bf16 v[60:63], v[132:135], v[148:151], v[60:63]
	v_mfma_f32_16x16x32_bf16 v[56:59], v[140:143], v[148:151], v[56:59]
	v_mfma_f32_16x16x32_bf16 v[56:59], v[136:139], v[144:147], v[56:59]
	v_mfma_f32_16x16x32_bf16 v[40:43], v[136:139], v[152:155], v[40:43]
	v_mfma_f32_16x16x32_bf16 v[40:43], v[140:143], v[156:159], v[40:43]
	v_mfma_f32_16x16x32_bf16 v[44:47], v[132:135], v[156:159], v[44:47]
	v_mfma_f32_16x16x32_bf16 v[44:47], v[128:131], v[152:155], v[44:47]
	v_mfma_f32_16x16x32_bf16 v[28:31], v[128:131], v[160:163], v[28:31]
	v_mfma_f32_16x16x32_bf16 v[28:31], v[132:135], v[164:167], v[28:31]
	v_mfma_f32_16x16x32_bf16 v[24:27], v[140:143], v[164:167], v[24:27]
	v_mfma_f32_16x16x32_bf16 v[24:27], v[136:139], v[160:163], v[24:27]
	v_mfma_f32_16x16x32_bf16 v[8:11], v[136:139], v[168:171], v[8:11]
	v_mfma_f32_16x16x32_bf16 v[8:11], v[140:143], v[172:175], v[8:11]
	v_mfma_f32_16x16x32_bf16 v[12:15], v[132:135], v[172:175], v[12:15]
	v_mfma_f32_16x16x32_bf16 v[12:15], v[128:131], v[168:171], v[12:15]
	s_setprio 0
	s_barrier
	s_add_u32 s70, s42, 0x40000
	s_addc_u32 s71, s43, 0
	s_add_i32 s69, s67, s51
	s_mov_b32 m0, s69
	s_nop 0
	global_load_lds_dwordx4 v178, s[70:71]
	s_add_i32 m0, s69, 0x2000
	s_nop 0
	global_load_lds_dwordx4 v182, s[70:71]
	s_waitcnt vmcnt(6)
	s_barrier
; #define PG8_STAGE(bufoff, gbase, voff) do { _Pragma("unroll") for (int _i = 0; _i < 2; ++_i) \
;         __builtin_amdgcn_global_load_lds((const unsigned*)((const char*)(gbase) + (voff)[_i]), (LAS unsigned*)(lds + (bufoff) + ldsw + _i * 8192), 16, 0, 0); } while (0)
; #define PG8_LDA(dst, b, h) do { _Pragma("unroll") for (int m = 0; m < 4; ++m) _Pragma("unroll") for (int k = 0; k < 2; ++k) dst[m][k] = *(const LAS bf16x8*)(lds + PG8_SA(b, h) + aoff + m * 2048 + k * 1024); } while (0)
; #define PG8_LDB(dst, b, h) do { _Pragma("unroll") for (int n = 0; n < 2; ++n) _Pragma("unroll") for (int k = 0; k < 2; ++k) dst[n][k] = *(const LAS bf16x8*)(lds + PG8_SB(b, h) + boff + n * 2048 + k * 1024); } while (0)
; #define PG8_MMA(ai, bj, At, Bt) do { __builtin_amdgcn_s_setprio(1); _Pragma("unroll") for (int m = 0; m < 4; ++m) _Pragma("unroll") for (int n = 0; n < 2; ++n) _Pragma("unroll") for (int k = 0; k < 2; ++k) \
;         acc[ai][bj][m][n] = __builtin_amdgcn_mfma_f32_16x16x32_bf16(Bt[n][k], At[m][k], acc[ai][bj][m][n], 0, 0, 0); __builtin_amdgcn_s_setprio(0); } while (0)
; #define PG8_WAIT_V(n) asm volatile("s_waitcnt vmcnt(" #n ")" ::: "memory")
; #define PG8_WAIT_L(n) asm volatile("s_waitcnt lgkmcnt(" #n ")" ::: "memory")
; #define PG8_BAR __builtin_amdgcn_s_barrier()
; #define PG8_SCHED __builtin_amdgcn_sched_barrier(0)
; template <class Epi, class Ptrs>
; __device__ __forceinline__ void gemm_phase(LAS unsigned char* lds, const int K, const StaticOrder& S, const Ptrs& P, const Epi& E) {
;     ...
;             PG8_WAIT_V(6); PG8_BAR; PG8_MMA(1, 1, At, B1); PG8_BAR;
;             PG8_LDB(B0, 1, 0); PG8_SCHED; PG8_LDA(At, 1, 0); PG8_STAGE(PG8_SA(0, 1), a2 + hstep, voffA);
;             PG8_WAIT_L(8); PG8_BAR; PG8_WAIT_L(0); PG8_MMA(0, 0, At, B0); PG8_BAR; PG8_SCHED;
;             PG8_LDB(B1, 1, 1); PG8_STAGE(PG8_SB(1, 0), b3, voffB);
;             PG8_BAR; PG8_WAIT_L(0); PG8_MMA(0, 1, At, B1); PG8_BAR;
;             PG8_LDA(At, 1, 1); PG8_STAGE(PG8_SA(1, 0), a3, voffA);
;             PG8_BAR; PG8_WAIT_L(0); PG8_MMA(1, 0, At, B0); PG8_BAR; PG8_SCHED;
	s_setprio 1
	v_mfma_f32_16x16x32_bf16 v[52:55], v[192:195], v[144:147], v[52:55]
	v_mfma_f32_16x16x32_bf16 v[52:55], v[196:199], v[148:151], v[52:55]
	v_mfma_f32_16x16x32_bf16 v[48:51], v[212:215], v[148:151], v[48:51]
	v_mfma_f32_16x16x32_bf16 v[48:51], v[200:203], v[144:147], v[48:51]
	v_mfma_f32_16x16x32_bf16 v[32:35], v[200:203], v[152:155], v[32:35]
	v_mfma_f32_16x16x32_bf16 v[32:35], v[212:215], v[156:159], v[32:35]
	v_mfma_f32_16x16x32_bf16 v[36:39], v[196:199], v[156:159], v[36:39]
	v_mfma_f32_16x16x32_bf16 v[36:39], v[192:195], v[152:155], v[36:39]
	v_mfma_f32_16x16x32_bf16 v[20:23], v[192:195], v[160:163], v[20:23]
	v_mfma_f32_16x16x32_bf16 v[20:23], v[196:199], v[164:167], v[20:23]
	v_mfma_f32_16x16x32_bf16 v[16:19], v[212:215], v[164:167], v[16:19]
	v_mfma_f32_16x16x32_bf16 v[16:19], v[200:203], v[160:163], v[16:19]
	v_mfma_f32_16x16x32_bf16 v[0:3], v[200:203], v[168:171], v[0:3]
	v_mfma_f32_16x16x32_bf16 v[0:3], v[212:215], v[172:175], v[0:3]
	v_mfma_f32_16x16x32_bf16 v[4:7], v[196:199], v[172:175], v[4:7]
	v_mfma_f32_16x16x32_bf16 v[4:7], v[192:195], v[168:171], v[4:7]
	s_setprio 0
	s_add_i32 s69, 0, 0x18000
	s_barrier
	ds_read_b128 v[128:131], v252
	ds_read_b128 v[132:135], v252 offset:1024
	ds_read_b128 v[136:139], v252 offset:2048
	ds_read_b128 v[140:143], v252 offset:3072
	s_add_u32 s44, s44, 0x40000
	s_addc_u32 s45, s45, 0
	s_mov_b32 m0, s56
	ds_read_b128 v[144:147], v209 offset:32768
	ds_read_b128 v[148:151], v209 offset:33792
	ds_read_b128 v[152:155], v209 offset:34816
	ds_read_b128 v[156:159], v209 offset:35840
	ds_read_b128 v[160:163], v209 offset:36864
	ds_read_b128 v[164:167], v209 offset:37888
	ds_read_b128 v[168:171], v209 offset:38912
	ds_read_b128 v[172:175], v209 offset:39936
	global_load_lds_dwordx4 v176, s[44:45]
	s_mov_b32 m0, s57
	s_nop 0
	global_load_lds_dwordx4 v180, s[44:45]
	s_waitcnt lgkmcnt(8)
	s_barrier
	s_waitcnt lgkmcnt(0)
	s_setprio 1
	s_waitcnt lgkmcnt(0)
	v_mfma_f32_16x16x32_bf16 v[124:127], v[128:131], v[144:147], v[124:127]
	v_mfma_f32_16x16x32_bf16 v[124:127], v[132:135], v[148:151], v[124:127]
	v_mfma_f32_16x16x32_bf16 v[120:123], v[140:143], v[148:151], v[120:123]
	v_mfma_f32_16x16x32_bf16 v[120:123], v[136:139], v[144:147], v[120:123]
	v_mfma_f32_16x16x32_bf16 v[104:107], v[136:139], v[152:155], v[104:107]
	v_mfma_f32_16x16x32_bf16 v[104:107], v[140:143], v[156:159], v[104:107]
	v_mfma_f32_16x16x32_bf16 v[108:111], v[132:135], v[156:159], v[108:111]
	v_mfma_f32_16x16x32_bf16 v[108:111], v[128:131], v[152:155], v[108:111]
	v_mfma_f32_16x16x32_bf16 v[92:95], v[128:131], v[160:163], v[92:95]
	v_mfma_f32_16x16x32_bf16 v[92:95], v[132:135], v[164:167], v[92:95]
	v_mfma_f32_16x16x32_bf16 v[88:91], v[140:143], v[164:167], v[88:91]
	v_mfma_f32_16x16x32_bf16 v[88:91], v[136:139], v[160:163], v[88:91]
	v_mfma_f32_16x16x32_bf16 v[72:75], v[136:139], v[168:171], v[72:75]
	v_mfma_f32_16x16x32_bf16 v[72:75], v[140:143], v[172:175], v[72:75]
	v_mfma_f32_16x16x32_bf16 v[76:79], v[132:135], v[172:175], v[76:79]
	v_mfma_f32_16x16x32_bf16 v[76:79], v[128:131], v[168:171], v[76:79]
	s_setprio 0
	s_barrier
	s_add_i32 s44, 0, 0x1c000
	s_add_i32 s45, s69, s51
	s_mov_b32 m0, s45
	ds_read_b128 v[192:195], v253
	ds_read_b128 v[196:199], v253 offset:1024
	ds_read_b128 v[200:203], v253 offset:2048
	ds_read_b128 v[212:215], v253 offset:3072
	global_load_lds_dwordx4 v178, s[90:91]
	s_add_i32 m0, s45, 0x2000
	s_nop 0
	global_load_lds_dwordx4 v182, s[90:91]
	s_barrier
	s_waitcnt lgkmcnt(0)
	s_setprio 1
	s_waitcnt lgkmcnt(0)
	v_mfma_f32_16x16x32_bf16 v[116:119], v[192:195], v[144:147], v[116:119]
	v_mfma_f32_16x16x32_bf16 v[116:119], v[196:199], v[148:151], v[116:119]
	v_mfma_f32_16x16x32_bf16 v[112:115], v[212:215], v[148:151], v[112:115]
	v_mfma_f32_16x16x32_bf16 v[112:115], v[200:203], v[144:147], v[112:115]
	v_mfma_f32_16x16x32_bf16 v[96:99], v[200:203], v[152:155], v[96:99]
	v_mfma_f32_16x16x32_bf16 v[96:99], v[212:215], v[156:159], v[96:99]
	v_mfma_f32_16x16x32_bf16 v[100:103], v[196:199], v[156:159], v[100:103]
	v_mfma_f32_16x16x32_bf16 v[100:103], v[192:195], v[152:155], v[100:103]
	v_mfma_f32_16x16x32_bf16 v[84:87], v[192:195], v[160:163], v[84:87]
	v_mfma_f32_16x16x32_bf16 v[84:87], v[196:199], v[164:167], v[84:87]
	v_mfma_f32_16x16x32_bf16 v[80:83], v[212:215], v[164:167], v[80:83]
	v_mfma_f32_16x16x32_bf16 v[80:83], v[200:203], v[160:163], v[80:83]
	v_mfma_f32_16x16x32_bf16 v[64:67], v[200:203], v[168:171], v[64:67]
	v_mfma_f32_16x16x32_bf16 v[64:67], v[212:215], v[172:175], v[64:67]
	v_mfma_f32_16x16x32_bf16 v[68:71], v[196:199], v[172:175], v[68:71]
	v_mfma_f32_16x16x32_bf16 v[68:71], v[192:195], v[168:171], v[68:71]
	s_setprio 0
	s_mov_b32 m0, s63
	s_barrier
	ds_read_b128 v[144:147], v209 offset:49152
	ds_read_b128 v[148:151], v209 offset:50176
	ds_read_b128 v[152:155], v209 offset:51200
	ds_read_b128 v[156:159], v209 offset:52224
	ds_read_b128 v[160:163], v209 offset:53248
	ds_read_b128 v[164:167], v209 offset:54272
	ds_read_b128 v[168:171], v209 offset:55296
	ds_read_b128 v[172:175], v209 offset:56320
	global_load_lds_dwordx4 v176, s[92:93]
	s_mov_b32 m0, s64
	s_nop 0
	global_load_lds_dwordx4 v180, s[92:93]
	s_barrier
; #define PG8_STAGE(bufoff, gbase, voff) do { _Pragma("unroll") for (int _i = 0; _i < 2; ++_i) \
;         __builtin_amdgcn_global_load_lds((const unsigned*)((const char*)(gbase) + (voff)[_i]), (LAS unsigned*)(lds + (bufoff) + ldsw + _i * 8192), 16, 0, 0); } while (0)
; #define PG8_MMA(ai, bj, At, Bt) do { __builtin_amdgcn_s_setprio(1); _Pragma("unroll") for (int m = 0; m < 4; ++m) _Pragma("unroll") for (int n = 0; n < 2; ++n) _Pragma("unroll") for (int k = 0; k < 2; ++k) \
;         acc[ai][bj][m][n] = __builtin_amdgcn_mfma_f32_16x16x32_bf16(Bt[n][k], At[m][k], acc[ai][bj][m][n], 0, 0, 0); __builtin_amdgcn_s_setprio(0); } while (0)
; #define PG8_WAIT_V(n) asm volatile("s_waitcnt vmcnt(" #n ")" ::: "memory")
; #define PG8_WAIT_L(n) asm volatile("s_waitcnt lgkmcnt(" #n ")" ::: "memory")
; #define PG8_BAR __builtin_amdgcn_s_barrier()
; #define PG8_SCHED __builtin_amdgcn_sched_barrier(0)
; template <class Epi, class Ptrs>
; __device__ __forceinline__ void gemm_phase(LAS unsigned char* lds, const int K, const StaticOrder& S, const Ptrs& P, const Epi& E) {
;     ...
;             PG8_BAR; PG8_WAIT_L(0); PG8_MMA(1, 0, At, B0); PG8_BAR; PG8_SCHED;
;             PG8_STAGE(PG8_SB(1, 1), b3 + hstep, voffB);
;             PG8_WAIT_V(6); PG8_BAR; PG8_MMA(1, 1, At, B1); PG8_BAR;
;         }
	s_waitcnt lgkmcnt(0)
	s_setprio 1
	s_waitcnt lgkmcnt(0)
	v_mfma_f32_16x16x32_bf16 v[60:63], v[128:131], v[144:147], v[60:63]
	v_mfma_f32_16x16x32_bf16 v[60:63], v[132:135], v[148:151], v[60:63]
	v_mfma_f32_16x16x32_bf16 v[56:59], v[140:143], v[148:151], v[56:59]
	v_mfma_f32_16x16x32_bf16 v[56:59], v[136:139], v[144:147], v[56:59]
	v_mfma_f32_16x16x32_bf16 v[40:43], v[136:139], v[152:155], v[40:43]
	v_mfma_f32_16x16x32_bf16 v[40:43], v[140:143], v[156:159], v[40:43]
	v_mfma_f32_16x16x32_bf16 v[44:47], v[132:135], v[156:159], v[44:47]
	v_mfma_f32_16x16x32_bf16 v[44:47], v[128:131], v[152:155], v[44:47]
	v_mfma_f32_16x16x32_bf16 v[28:31], v[128:131], v[160:163], v[28:31]
	v_mfma_f32_16x16x32_bf16 v[28:31], v[132:135], v[164:167], v[28:31]
	v_mfma_f32_16x16x32_bf16 v[24:27], v[140:143], v[164:167], v[24:27]
	v_mfma_f32_16x16x32_bf16 v[24:27], v[136:139], v[160:163], v[24:27]
	v_mfma_f32_16x16x32_bf16 v[8:11], v[136:139], v[168:171], v[8:11]
	v_mfma_f32_16x16x32_bf16 v[8:11], v[140:143], v[172:175], v[8:11]
	v_mfma_f32_16x16x32_bf16 v[12:15], v[132:135], v[172:175], v[12:15]
	v_mfma_f32_16x16x32_bf16 v[12:15], v[128:131], v[168:171], v[12:15]
	s_setprio 0
	s_barrier
	s_add_u32 s42, s42, 0x40080
	s_addc_u32 s43, s43, 0
	s_add_i32 s44, s44, s51
	s_mov_b32 m0, s44
	s_nop 0
	global_load_lds_dwordx4 v178, s[42:43]
	s_add_i32 m0, s44, 0x2000
	s_nop 0
	global_load_lds_dwordx4 v182, s[42:43]
	s_waitcnt vmcnt(6)
	s_barrier
	s_setprio 1
	v_mfma_f32_16x16x32_bf16 v[52:55], v[192:195], v[144:147], v[52:55]
	v_mfma_f32_16x16x32_bf16 v[52:55], v[196:199], v[148:151], v[52:55]
	v_mfma_f32_16x16x32_bf16 v[48:51], v[212:215], v[148:151], v[48:51]
	v_mfma_f32_16x16x32_bf16 v[48:51], v[200:203], v[144:147], v[48:51]
	v_mfma_f32_16x16x32_bf16 v[32:35], v[200:203], v[152:155], v[32:35]
	v_mfma_f32_16x16x32_bf16 v[32:35], v[212:215], v[156:159], v[32:35]
	v_mfma_f32_16x16x32_bf16 v[36:39], v[196:199], v[156:159], v[36:39]
	v_mfma_f32_16x16x32_bf16 v[36:39], v[192:195], v[152:155], v[36:39]
	v_mfma_f32_16x16x32_bf16 v[20:23], v[192:195], v[160:163], v[20:23]
	v_mfma_f32_16x16x32_bf16 v[20:23], v[196:199], v[164:167], v[20:23]
	v_mfma_f32_16x16x32_bf16 v[16:19], v[212:215], v[164:167], v[16:19]
	v_mfma_f32_16x16x32_bf16 v[16:19], v[200:203], v[160:163], v[16:19]
	v_mfma_f32_16x16x32_bf16 v[0:3], v[200:203], v[168:171], v[0:3]
	v_mfma_f32_16x16x32_bf16 v[0:3], v[212:215], v[172:175], v[0:3]
	v_mfma_f32_16x16x32_bf16 v[4:7], v[196:199], v[172:175], v[4:7]
	v_mfma_f32_16x16x32_bf16 v[4:7], v[192:195], v[168:171], v[4:7]
	s_setprio 0
	s_add_i32 s41, s41, 2
	s_add_u32 s38, s38, 0x100
	s_addc_u32 s39, s39, 0
	s_add_u32 s21, s21, 0x100
	s_addc_u32 s23, s23, 0
	s_cmp_gt_u32 s41, 13
	s_barrier
	s_cbranch_scc0 .LBB0_353
; __device__ __forceinline__ unsigned cvt_pk_bf16(float lo, float hi) { unsigned r; asm volatile("v_cvt_pk_bf16_f32 %0, %1, %2" : "=v"(r) : "v"(lo), "v"(hi)); return r; }
; __device__ __forceinline__ float x16_sum(float x) { auto s = __builtin_amdgcn_permlane16_swap(__float_as_uint(x), __float_as_uint(x), false, false); return __uint_as_float(s[0]) + __uint_as_float(s[1]); }
; __device__ __forceinline__ float x32_sum(float x) { auto s = __builtin_amdgcn_permlane32_swap(__float_as_uint(x), __float_as_uint(x), false, false); return __uint_as_float(s[0]) + __uint_as_float(s[1]); }
;     __device__ __forceinline__ void operator()(const f32x4 (&acc)[2][2][4][2], const Unit& u, int ui, int wr, int wc, int fr, int fq) const {
;         const int row0 = u.pm * 256 + wr * 64 + fr, col0 = u.pn * 256 + wc * 32 + 8 * fq;
;         const float* xb0 = (u.pm * 256 < MP) ? xp : xs - (size_t)MP * DM;
; #pragma unroll
;         for (int ai = 0; ai < 2; ++ai) {
;             f32x4 xv[4][2][2];
; #pragma unroll
;             for (int m = 0; m < 4; ++m)
; #pragma unroll
;                 for (int bj = 0; bj < 2; ++bj) { const float* p = xb0 + (size_t)(row0 + ai * 128 + m * 16) * DM + col0 + bj * 128; xv[m][bj][0] = *(const f32x4*)p; xv[m][bj][1] = *(const f32x4*)(p + 4); }
; #pragma unroll
;             for (int m = 0; m < 4; ++m) { const int row = row0 + ai * 128 + m * 16; const size_t off = (size_t)row * DM + col0; float ss = 0.f;
; #pragma unroll
;                 for (int bj = 0; bj < 2; ++bj) {
;                     const f32x4 v0 = acc[ai][bj][m][0] + xv[m][bj][0], v1 = acc[ai][bj][m][1] + xv[m][bj][1];
;                     u32x4 w; w.x = cvt_pk_bf16(v0[0], v0[1]); w.y = cvt_pk_bf16(v0[2], v0[3]); w.z = cvt_pk_bf16(v1[0], v1[1]); w.w = cvt_pk_bf16(v1[2], v1[3]);
;                     *(u32x4*)(xb + off + bj * 128) = w;
;                     ss += (v0[0] * v0[0] + v0[1] * v0[1]) + (v0[2] * v0[2] + v0[3] * v0[3]) + (v1[0] * v1[0] + v1[1] * v1[1]) + (v1[2] * v1[2] + v1[3] * v1[3]); }
;                 ss = x32_sum(x16_sum(ss));
;                 if (fq == 0) part[(size_t)row * 16 + u.pn * 4 + wc] = ss; }
	s_nop 0
	s_nop 0
	s_nop 0
	s_nop 0
	s_nop 0
	s_nop 0
	s_nop 0
	s_nop 0
	s_nop 0
	s_nop 0
	s_nop 0
	s_nop 0
	s_nop 0
	s_nop 0
	s_nop 0
	s_nop 0
	s_nop 0
	s_nop 0
	s_nop 0
	s_nop 0
	s_nop 0
	s_nop 0
	s_nop 0
	s_nop 0
	s_nop 0
	s_nop 0
	s_nop 0
	s_nop 0
	s_cmpk_lt_i32 s40, 0x80
	v_lshl_add_u32 v194, s40, 8, v204
	v_lshl_or_b32 v192, s12, 8, v206
	s_cselect_b32 s21, s37, s61
	s_cselect_b32 s23, s36, s60
	v_mov_b32_e32 v128, s23
	v_mov_b32_e32 v129, s21
	v_ashrrev_i32_e32 v193, 31, v192
	v_ashrrev_i32_e32 v195, 31, v194
	v_lshl_add_u64 v[196:197], v[192:193], 2, v[128:129]
	v_lshlrev_b64 v[128:129], 12, v[194:195]
	v_or_b32_e32 v202, 16, v194
	v_or_b32_e32 v200, 32, v194
	v_or_b32_e32 v198, 48, v194
	v_lshl_add_u64 v[128:129], v[196:197], 0, v[128:129]
	v_ashrrev_i32_e32 v203, 31, v202
	v_ashrrev_i32_e32 v201, 31, v200
	v_ashrrev_i32_e32 v199, 31, v198
	global_load_dwordx4 v[212:215], v[128:129], off
	global_load_dwordx4 v[216:219], v[128:129], off offset:16
	global_load_dwordx4 v[220:223], v[128:129], off offset:512
	global_load_dwordx4 v[224:227], v[128:129], off offset:528
	v_lshlrev_b64 v[128:129], 12, v[202:203]
	v_lshlrev_b64 v[130:131], 12, v[200:201]
	v_lshlrev_b64 v[132:133], 12, v[198:199]
	v_lshl_add_u64 v[128:129], v[196:197], 0, v[128:129]
	v_lshl_add_u64 v[130:131], v[196:197], 0, v[130:131]
	v_lshl_add_u64 v[132:133], v[196:197], 0, v[132:133]
	global_load_dwordx4 v[168:171], v[128:129], off offset:16
	global_load_dwordx4 v[172:175], v[128:129], off
	global_load_dwordx4 v[160:163], v[128:129], off offset:528
	global_load_dwordx4 v[164:167], v[128:129], off offset:512
	global_load_dwordx4 v[152:155], v[130:131], off offset:16
	global_load_dwordx4 v[156:159], v[130:131], off
	global_load_dwordx4 v[144:147], v[130:131], off offset:528
	global_load_dwordx4 v[148:151], v[130:131], off offset:512
	global_load_dwordx4 v[136:139], v[132:133], off offset:16
	global_load_dwordx4 v[140:143], v[132:133], off
	s_nop 0
	global_load_dwordx4 v[128:131], v[132:133], off offset:528
	s_nop 0
	global_load_dwordx4 v[132:135], v[132:133], off offset:512
	v_lshlrev_b64 v[228:229], 11, v[194:195]
	v_lshl_add_u64 v[228:229], s[14:15], 0, v[228:229]
	v_lshl_add_u64 v[228:229], v[192:193], 1, v[228:229]
	s_lshl_b32 s38, s12, 2
	s_ashr_i32 s39, s38, 31
	s_waitcnt vmcnt(0)
	v_pk_add_f32 v[126:127], v[126:127], v[214:215]
	v_pk_add_f32 v[124:125], v[124:125], v[212:213]
	v_pk_add_f32 v[118:119], v[118:119], v[222:223]
	v_pk_add_f32 v[116:117], v[116:117], v[220:221]
	v_pk_add_f32 v[120:121], v[120:121], v[216:217]
	v_pk_add_f32 v[214:215], v[112:113], v[224:225]
	v_cvt_pk_bf16_f32 v112, v124, v125
	v_cvt_pk_bf16_f32 v113, v126, v127
	v_mul_f32_e32 v125, v125, v125
	v_mul_f32_e32 v127, v127, v127
	v_mul_f32_e32 v211, v117, v117
	v_mul_f32_e32 v216, v119, v119
	v_pk_add_f32 v[122:123], v[122:123], v[218:219]
	v_pk_add_f32 v[212:213], v[114:115], v[226:227]
	v_cvt_pk_bf16_f32 v114, v120, v121
	v_cvt_pk_bf16_f32 v115, v122, v123
	v_mul_f32_e32 v121, v121, v121
	v_mul_f32_e32 v217, v215, v215
	global_store_dwordx4 v[228:229], v[112:115], off
	v_fmac_f32_e32 v125, v124, v124
	v_fmac_f32_e32 v127, v126, v126
	v_cvt_pk_bf16_f32 v112, v116, v117
	v_fmac_f32_e32 v211, v116, v116
	v_fmac_f32_e32 v216, v118, v118
	v_mul_f32_e32 v123, v123, v123
	v_mul_f32_e32 v218, v213, v213
	v_fmac_f32_e32 v121, v120, v120
	v_cvt_pk_bf16_f32 v113, v118, v119
	v_cvt_pk_bf16_f32 v114, v214, v215
	v_cvt_pk_bf16_f32 v115, v212, v213
	v_fmac_f32_e32 v217, v214, v214
	v_add_f32_e32 v116, v125, v127
	global_store_dwordx4 v[228:229], v[112:115], off offset:256
	v_fmac_f32_e32 v123, v122, v122
	v_fmac_f32_e32 v218, v212, v212
	v_add_f32_e32 v112, v211, v216
	v_add_f32_e32 v113, v116, v121
	v_add_f32_e32 v112, v112, v217
	v_add_f32_e32 v113, v123, v113
	v_add_f32_e32 v112, v218, v112
	v_add_f32_e32 v112, v113, v112
	v_mov_b32_e32 v113, v112
	s_nop 1
	v_permlane16_swap_b32_e32 v112, v113
	v_add_f32_e32 v112, v112, v113
	v_mov_b32_e32 v113, v112
	s_nop 1
	v_permlane32_swap_b32_e32 v112, v113
	s_and_saveexec_b64 s[40:41], s[6:7]
	s_cbranch_execz .LBB0_356
	v_lshlrev_b64 v[114:115], 6, v[194:195]
	v_lshl_add_u64 v[114:115], s[16:17], 0, v[114:115]
	v_lshl_add_u64 v[114:115], s[38:39], 2, v[114:115]
	s_lshl_b32 s12, s62, 2
	v_lshl_add_u64 v[114:115], v[114:115], 0, s[12:13]
	v_add_f32_e32 v112, v112, v113
	global_store_dword v[114:115], v112, off

; #define PG8_STAGE(bufoff, gbase, voff) do { _Pragma("unroll") for (int _i = 0; _i < 2; ++_i) \
;         __builtin_amdgcn_global_load_lds((const unsigned*)((const char*)(gbase) + (voff)[_i]), (LAS unsigned*)(lds + (bufoff) + ldsw + _i * 8192), 16, 0, 0); } while (0)
; #define PG8_LDA(dst, b, h) do { _Pragma("unroll") for (int m = 0; m < 4; ++m) _Pragma("unroll") for (int k = 0; k < 2; ++k) dst[m][k] = *(const LAS bf16x8*)(lds + PG8_SA(b, h) + aoff + m * 2048 + k * 1024); } while (0)
; #define PG8_LDB(dst, b, h) do { _Pragma("unroll") for (int n = 0; n < 2; ++n) _Pragma("unroll") for (int k = 0; k < 2; ++k) dst[n][k] = *(const LAS bf16x8*)(lds + PG8_SB(b, h) + boff + n * 2048 + k * 1024); } while (0)
; #define PG8_MMA(ai, bj, At, Bt) do { __builtin_amdgcn_s_setprio(1); _Pragma("unroll") for (int m = 0; m < 4; ++m) _Pragma("unroll") for (int n = 0; n < 2; ++n) _Pragma("unroll") for (int k = 0; k < 2; ++k) \
;         acc[ai][bj][m][n] = __builtin_amdgcn_mfma_f32_16x16x32_bf16(Bt[n][k], At[m][k], acc[ai][bj][m][n], 0, 0, 0); __builtin_amdgcn_s_setprio(0); } while (0)
; #define PG8_WAIT_V(n) asm volatile("s_waitcnt vmcnt(" #n ")" ::: "memory")
; #define PG8_WAIT_L(n) asm volatile("s_waitcnt lgkmcnt(" #n ")" ::: "memory")
; template <class Epi, class Ptrs>
; __device__ __forceinline__ void gemm_phase(LAS unsigned char* lds, const int K, const StaticOrder& S, const Ptrs& P, const Epi& E) {
;     ...
;         for (int t = 0; t < nt; t += 2) {
;             const bool last = (t == nt - 2);
;             const char* a1 = cA + (size_t)(t + 1) * kstep;
;             const char* a2 = last ? nA : cA + (size_t)(t + 2) * kstep; const char* b2 = last ? nB : cB + (size_t)(t + 2) * kstep;
;             const char* a3 = a2 + kstep; const char* b3 = b2 + kstep;
;             PG8_LDB(B0, 0, 0); PG8_SCHED; PG8_LDA(At, 0, 0); PG8_STAGE(PG8_SA(1, 1), a1 + hstep, voffA);
;             PG8_WAIT_L(8); PG8_BAR; PG8_WAIT_L(0); PG8_MMA(0, 0, At, B0); PG8_BAR; PG8_SCHED;
;             PG8_LDB(B1, 0, 1); PG8_STAGE(PG8_SB(0, 0), b2, voffB);
;             PG8_BAR; PG8_WAIT_L(0); PG8_MMA(0, 1, At, B1); PG8_BAR;
;             PG8_LDA(At, 0, 1); PG8_STAGE(PG8_SA(0, 0), a2, voffA);
;             PG8_BAR; PG8_WAIT_L(0); PG8_MMA(1, 0, At, B0); PG8_BAR; PG8_SCHED;
;             PG8_STAGE(PG8_SB(0, 1), b2 + hstep, voffB);
;             PG8_WAIT_V(6); PG8_BAR; PG8_MMA(1, 1, At, B1); PG8_BAR;
.LBB0_433:
	ds_read_b128 v[152:155], v149
	ds_read_b128 v[156:159], v149 offset:1024
	ds_read_b128 v[160:163], v149 offset:2048
	ds_read_b128 v[164:167], v149 offset:3072
	s_add_u32 s42, s40, 0xfffc0080
	s_addc_u32 s43, s41, -1
	s_cmp_eq_u32 s70, 12
	s_cselect_b32 s45, s1, s43
	s_cselect_b32 s44, s0, s42
	s_cselect_b32 s43, s37, s25
	s_cselect_b32 s42, s36, s23
	s_add_i32 m0, s39, 0xc000
	ds_read_b128 v[168:171], v150
	ds_read_b128 v[172:175], v150 offset:1024
	ds_read_b128 v[176:179], v150 offset:2048
	ds_read_b128 v[180:183], v150 offset:3072
	ds_read_b128 v[184:187], v150 offset:4096
	ds_read_b128 v[188:191], v150 offset:5120
	ds_read_b128 v[192:195], v150 offset:6144
	ds_read_b128 v[196:199], v150 offset:7168
	global_load_lds_dwordx4 v136, s[40:41]
	s_add_i32 m0, s39, 0xe000
	s_nop 0
	global_load_lds_dwordx4 v138, s[40:41]
	s_waitcnt lgkmcnt(8)
	s_barrier
	s_waitcnt lgkmcnt(0)
	s_setprio 1
	s_waitcnt lgkmcnt(0)
	v_mfma_f32_16x16x32_bf16 v[124:127], v[152:155], v[168:171], v[124:127]
	v_mfma_f32_16x16x32_bf16 v[124:127], v[156:159], v[172:175], v[124:127]
	v_mfma_f32_16x16x32_bf16 v[120:123], v[164:167], v[172:175], v[120:123]
	v_mfma_f32_16x16x32_bf16 v[120:123], v[160:163], v[168:171], v[120:123]
	v_mfma_f32_16x16x32_bf16 v[104:107], v[160:163], v[176:179], v[104:107]
	v_mfma_f32_16x16x32_bf16 v[104:107], v[164:167], v[180:183], v[104:107]
	v_mfma_f32_16x16x32_bf16 v[108:111], v[156:159], v[180:183], v[108:111]
	v_mfma_f32_16x16x32_bf16 v[108:111], v[152:155], v[176:179], v[108:111]
	v_mfma_f32_16x16x32_bf16 v[92:95], v[152:155], v[184:187], v[92:95]
	v_mfma_f32_16x16x32_bf16 v[92:95], v[156:159], v[188:191], v[92:95]
	v_mfma_f32_16x16x32_bf16 v[88:91], v[164:167], v[188:191], v[88:91]
	v_mfma_f32_16x16x32_bf16 v[88:91], v[160:163], v[184:187], v[88:91]
	v_mfma_f32_16x16x32_bf16 v[72:75], v[160:163], v[192:195], v[72:75]
	v_mfma_f32_16x16x32_bf16 v[72:75], v[164:167], v[196:199], v[72:75]
	v_mfma_f32_16x16x32_bf16 v[76:79], v[156:159], v[196:199], v[76:79]
	v_mfma_f32_16x16x32_bf16 v[76:79], v[152:155], v[192:195], v[76:79]
	s_setprio 0
	s_barrier
	s_add_i32 s71, s63, s51
	s_add_u32 s76, s42, 0x80
	s_addc_u32 s77, s43, 0
	s_mov_b32 m0, s71
	ds_read_b128 v[200:203], v151
	ds_read_b128 v[204:207], v151 offset:1024
	ds_read_b128 v[210:213], v151 offset:2048
	ds_read_b128 v[214:217], v151 offset:3072
	global_load_lds_dwordx4 v130, s[42:43]
	s_add_i32 m0, s71, 0x2000
	s_nop 0
	global_load_lds_dwordx4 v134, s[42:43]
	s_barrier
	s_waitcnt lgkmcnt(0)
	s_setprio 1
	s_waitcnt lgkmcnt(0)
	v_mfma_f32_16x16x32_bf16 v[116:119], v[200:203], v[168:171], v[116:119]
	v_mfma_f32_16x16x32_bf16 v[116:119], v[204:207], v[172:175], v[116:119]
	v_mfma_f32_16x16x32_bf16 v[112:115], v[214:217], v[172:175], v[112:115]
	v_mfma_f32_16x16x32_bf16 v[112:115], v[210:213], v[168:171], v[112:115]
	v_mfma_f32_16x16x32_bf16 v[96:99], v[210:213], v[176:179], v[96:99]
	v_mfma_f32_16x16x32_bf16 v[96:99], v[214:217], v[180:183], v[96:99]
	v_mfma_f32_16x16x32_bf16 v[100:103], v[204:207], v[180:183], v[100:103]
	v_mfma_f32_16x16x32_bf16 v[100:103], v[200:203], v[176:179], v[100:103]
	v_mfma_f32_16x16x32_bf16 v[84:87], v[200:203], v[184:187], v[84:87]
	v_mfma_f32_16x16x32_bf16 v[84:87], v[204:207], v[188:191], v[84:87]
	v_mfma_f32_16x16x32_bf16 v[80:83], v[214:217], v[188:191], v[80:83]
	v_mfma_f32_16x16x32_bf16 v[80:83], v[210:213], v[184:187], v[80:83]
	v_mfma_f32_16x16x32_bf16 v[64:67], v[210:213], v[192:195], v[64:67]
	v_mfma_f32_16x16x32_bf16 v[64:67], v[214:217], v[196:199], v[64:67]
	v_mfma_f32_16x16x32_bf16 v[68:71], v[204:207], v[196:199], v[68:71]
	v_mfma_f32_16x16x32_bf16 v[68:71], v[200:203], v[192:195], v[68:71]
	s_setprio 0
	s_mov_b32 m0, s39
	s_add_u32 s78, s44, 0x80
	s_addc_u32 s79, s45, 0
	s_barrier
	ds_read_b128 v[168:171], v150 offset:16384
	ds_read_b128 v[172:175], v150 offset:17408
	ds_read_b128 v[176:179], v150 offset:18432
	ds_read_b128 v[180:183], v150 offset:19456
	ds_read_b128 v[184:187], v150 offset:20480
	ds_read_b128 v[188:191], v150 offset:21504
	ds_read_b128 v[192:195], v150 offset:22528
	ds_read_b128 v[196:199], v150 offset:23552
	global_load_lds_dwordx4 v128, s[44:45]
	s_mov_b32 m0, s56
	s_nop 0
	global_load_lds_dwordx4 v132, s[44:45]
	s_barrier
	s_waitcnt lgkmcnt(0)
	s_setprio 1
	s_waitcnt lgkmcnt(0)
	v_mfma_f32_16x16x32_bf16 v[60:63], v[152:155], v[168:171], v[60:63]
	v_mfma_f32_16x16x32_bf16 v[60:63], v[156:159], v[172:175], v[60:63]
	v_mfma_f32_16x16x32_bf16 v[56:59], v[164:167], v[172:175], v[56:59]
	v_mfma_f32_16x16x32_bf16 v[56:59], v[160:163], v[168:171], v[56:59]
	v_mfma_f32_16x16x32_bf16 v[40:43], v[160:163], v[176:179], v[40:43]
	v_mfma_f32_16x16x32_bf16 v[40:43], v[164:167], v[180:183], v[40:43]
	v_mfma_f32_16x16x32_bf16 v[44:47], v[156:159], v[180:183], v[44:47]
	v_mfma_f32_16x16x32_bf16 v[44:47], v[152:155], v[176:179], v[44:47]
	v_mfma_f32_16x16x32_bf16 v[28:31], v[152:155], v[184:187], v[28:31]
	v_mfma_f32_16x16x32_bf16 v[28:31], v[156:159], v[188:191], v[28:31]
	v_mfma_f32_16x16x32_bf16 v[24:27], v[164:167], v[188:191], v[24:27]
	v_mfma_f32_16x16x32_bf16 v[24:27], v[160:163], v[184:187], v[24:27]
	v_mfma_f32_16x16x32_bf16 v[8:11], v[160:163], v[192:195], v[8:11]
	v_mfma_f32_16x16x32_bf16 v[8:11], v[164:167], v[196:199], v[8:11]
	v_mfma_f32_16x16x32_bf16 v[12:15], v[156:159], v[196:199], v[12:15]
	v_mfma_f32_16x16x32_bf16 v[12:15], v[152:155], v[192:195], v[12:15]
	s_setprio 0
	s_barrier
	s_add_u32 s72, s42, 0x40000
	s_addc_u32 s73, s43, 0
	s_add_i32 s71, s64, s51
	s_mov_b32 m0, s71
	s_nop 0
	global_load_lds_dwordx4 v130, s[72:73]
	s_add_i32 m0, s71, 0x2000
	s_nop 0
	global_load_lds_dwordx4 v134, s[72:73]
	s_waitcnt vmcnt(6)
	s_barrier
; #define PG8_STAGE(bufoff, gbase, voff) do { _Pragma("unroll") for (int _i = 0; _i < 2; ++_i) \
;         __builtin_amdgcn_global_load_lds((const unsigned*)((const char*)(gbase) + (voff)[_i]), (LAS unsigned*)(lds + (bufoff) + ldsw + _i * 8192), 16, 0, 0); } while (0)
; #define PG8_LDA(dst, b, h) do { _Pragma("unroll") for (int m = 0; m < 4; ++m) _Pragma("unroll") for (int k = 0; k < 2; ++k) dst[m][k] = *(const LAS bf16x8*)(lds + PG8_SA(b, h) + aoff + m * 2048 + k * 1024); } while (0)
; #define PG8_LDB(dst, b, h) do { _Pragma("unroll") for (int n = 0; n < 2; ++n) _Pragma("unroll") for (int k = 0; k < 2; ++k) dst[n][k] = *(const LAS bf16x8*)(lds + PG8_SB(b, h) + boff + n * 2048 + k * 1024); } while (0)
; #define PG8_MMA(ai, bj, At, Bt) do { __builtin_amdgcn_s_setprio(1); _Pragma("unroll") for (int m = 0; m < 4; ++m) _Pragma("unroll") for (int n = 0; n < 2; ++n) _Pragma("unroll") for (int k = 0; k < 2; ++k) \
;         acc[ai][bj][m][n] = __builtin_amdgcn_mfma_f32_16x16x32_bf16(Bt[n][k], At[m][k], acc[ai][bj][m][n], 0, 0, 0); __builtin_amdgcn_s_setprio(0); } while (0)
; #define PG8_WAIT_V(n) asm volatile("s_waitcnt vmcnt(" #n ")" ::: "memory")
; #define PG8_WAIT_L(n) asm volatile("s_waitcnt lgkmcnt(" #n ")" ::: "memory")
; #define PG8_BAR __builtin_amdgcn_s_barrier()
; #define PG8_SCHED __builtin_amdgcn_sched_barrier(0)
; template <class Epi, class Ptrs>
; __device__ __forceinline__ void gemm_phase(LAS unsigned char* lds, const int K, const StaticOrder& S, const Ptrs& P, const Epi& E) {
;     ...
;             PG8_WAIT_V(6); PG8_BAR; PG8_MMA(1, 1, At, B1); PG8_BAR;
;             PG8_LDB(B0, 1, 0); PG8_SCHED; PG8_LDA(At, 1, 0); PG8_STAGE(PG8_SA(0, 1), a2 + hstep, voffA);
;             PG8_WAIT_L(8); PG8_BAR; PG8_WAIT_L(0); PG8_MMA(0, 0, At, B0); PG8_BAR; PG8_SCHED;
;             PG8_LDB(B1, 1, 1); PG8_STAGE(PG8_SB(1, 0), b3, voffB);
;             PG8_BAR; PG8_WAIT_L(0); PG8_MMA(0, 1, At, B1); PG8_BAR;
;             PG8_LDA(At, 1, 1); PG8_STAGE(PG8_SA(1, 0), a3, voffA);
;             PG8_BAR; PG8_WAIT_L(0); PG8_MMA(1, 0, At, B0); PG8_BAR; PG8_SCHED;
	s_setprio 1
	v_mfma_f32_16x16x32_bf16 v[52:55], v[200:203], v[168:171], v[52:55]
	v_mfma_f32_16x16x32_bf16 v[52:55], v[204:207], v[172:175], v[52:55]
	v_mfma_f32_16x16x32_bf16 v[48:51], v[214:217], v[172:175], v[48:51]
	v_mfma_f32_16x16x32_bf16 v[48:51], v[210:213], v[168:171], v[48:51]
	v_mfma_f32_16x16x32_bf16 v[32:35], v[210:213], v[176:179], v[32:35]
	v_mfma_f32_16x16x32_bf16 v[32:35], v[214:217], v[180:183], v[32:35]
	v_mfma_f32_16x16x32_bf16 v[36:39], v[204:207], v[180:183], v[36:39]
	v_mfma_f32_16x16x32_bf16 v[36:39], v[200:203], v[176:179], v[36:39]
	v_mfma_f32_16x16x32_bf16 v[20:23], v[200:203], v[184:187], v[20:23]
	v_mfma_f32_16x16x32_bf16 v[20:23], v[204:207], v[188:191], v[20:23]
	v_mfma_f32_16x16x32_bf16 v[16:19], v[214:217], v[188:191], v[16:19]
	v_mfma_f32_16x16x32_bf16 v[16:19], v[210:213], v[184:187], v[16:19]
	v_mfma_f32_16x16x32_bf16 v[0:3], v[210:213], v[192:195], v[0:3]
	v_mfma_f32_16x16x32_bf16 v[0:3], v[214:217], v[196:199], v[0:3]
	v_mfma_f32_16x16x32_bf16 v[4:7], v[204:207], v[196:199], v[4:7]
	v_mfma_f32_16x16x32_bf16 v[4:7], v[200:203], v[192:195], v[4:7]
	s_setprio 0
	s_add_i32 s71, 0, 0x18000
	s_barrier
	ds_read_b128 v[152:155], v252
	ds_read_b128 v[156:159], v252 offset:1024
	ds_read_b128 v[160:163], v252 offset:2048
	ds_read_b128 v[164:167], v252 offset:3072
	s_add_u32 s44, s44, 0x40000
	s_addc_u32 s45, s45, 0
	s_mov_b32 m0, s57
	ds_read_b128 v[168:171], v150 offset:32768
	ds_read_b128 v[172:175], v150 offset:33792
	ds_read_b128 v[176:179], v150 offset:34816
	ds_read_b128 v[180:183], v150 offset:35840
	ds_read_b128 v[184:187], v150 offset:36864
	ds_read_b128 v[188:191], v150 offset:37888
	ds_read_b128 v[192:195], v150 offset:38912
	ds_read_b128 v[196:199], v150 offset:39936
	global_load_lds_dwordx4 v128, s[44:45]
	s_mov_b32 m0, s58
	s_nop 0
	global_load_lds_dwordx4 v132, s[44:45]
	s_waitcnt lgkmcnt(8)
	s_barrier
	s_waitcnt lgkmcnt(0)
	s_setprio 1
	s_waitcnt lgkmcnt(0)
	v_mfma_f32_16x16x32_bf16 v[124:127], v[152:155], v[168:171], v[124:127]
	v_mfma_f32_16x16x32_bf16 v[124:127], v[156:159], v[172:175], v[124:127]
	v_mfma_f32_16x16x32_bf16 v[120:123], v[164:167], v[172:175], v[120:123]
	v_mfma_f32_16x16x32_bf16 v[120:123], v[160:163], v[168:171], v[120:123]
	v_mfma_f32_16x16x32_bf16 v[104:107], v[160:163], v[176:179], v[104:107]
	v_mfma_f32_16x16x32_bf16 v[104:107], v[164:167], v[180:183], v[104:107]
	v_mfma_f32_16x16x32_bf16 v[108:111], v[156:159], v[180:183], v[108:111]
	v_mfma_f32_16x16x32_bf16 v[108:111], v[152:155], v[176:179], v[108:111]
	v_mfma_f32_16x16x32_bf16 v[92:95], v[152:155], v[184:187], v[92:95]
	v_mfma_f32_16x16x32_bf16 v[92:95], v[156:159], v[188:191], v[92:95]
	v_mfma_f32_16x16x32_bf16 v[88:91], v[164:167], v[188:191], v[88:91]
	v_mfma_f32_16x16x32_bf16 v[88:91], v[160:163], v[184:187], v[88:91]
	v_mfma_f32_16x16x32_bf16 v[72:75], v[160:163], v[192:195], v[72:75]
	v_mfma_f32_16x16x32_bf16 v[72:75], v[164:167], v[196:199], v[72:75]
	v_mfma_f32_16x16x32_bf16 v[76:79], v[156:159], v[196:199], v[76:79]
	v_mfma_f32_16x16x32_bf16 v[76:79], v[152:155], v[192:195], v[76:79]
	s_setprio 0
	s_barrier
	s_add_i32 s44, 0, 0x1c000
	s_add_i32 s45, s71, s51
	s_mov_b32 m0, s45
	ds_read_b128 v[200:203], v253
	ds_read_b128 v[204:207], v253 offset:1024
	ds_read_b128 v[210:213], v253 offset:2048
	ds_read_b128 v[214:217], v253 offset:3072
	global_load_lds_dwordx4 v130, s[76:77]
	s_add_i32 m0, s45, 0x2000
	s_nop 0
	global_load_lds_dwordx4 v134, s[76:77]
	s_barrier
	s_waitcnt lgkmcnt(0)
	s_setprio 1
	s_waitcnt lgkmcnt(0)
	v_mfma_f32_16x16x32_bf16 v[116:119], v[200:203], v[168:171], v[116:119]
	v_mfma_f32_16x16x32_bf16 v[116:119], v[204:207], v[172:175], v[116:119]
	v_mfma_f32_16x16x32_bf16 v[112:115], v[214:217], v[172:175], v[112:115]
	v_mfma_f32_16x16x32_bf16 v[112:115], v[210:213], v[168:171], v[112:115]
	v_mfma_f32_16x16x32_bf16 v[96:99], v[210:213], v[176:179], v[96:99]
	v_mfma_f32_16x16x32_bf16 v[96:99], v[214:217], v[180:183], v[96:99]
	v_mfma_f32_16x16x32_bf16 v[100:103], v[204:207], v[180:183], v[100:103]
	v_mfma_f32_16x16x32_bf16 v[100:103], v[200:203], v[176:179], v[100:103]
	v_mfma_f32_16x16x32_bf16 v[84:87], v[200:203], v[184:187], v[84:87]
	v_mfma_f32_16x16x32_bf16 v[84:87], v[204:207], v[188:191], v[84:87]
	v_mfma_f32_16x16x32_bf16 v[80:83], v[214:217], v[188:191], v[80:83]
	v_mfma_f32_16x16x32_bf16 v[80:83], v[210:213], v[184:187], v[80:83]
	v_mfma_f32_16x16x32_bf16 v[64:67], v[210:213], v[192:195], v[64:67]
	v_mfma_f32_16x16x32_bf16 v[64:67], v[214:217], v[196:199], v[64:67]
	v_mfma_f32_16x16x32_bf16 v[68:71], v[204:207], v[196:199], v[68:71]
	v_mfma_f32_16x16x32_bf16 v[68:71], v[200:203], v[192:195], v[68:71]
	s_setprio 0
	s_mov_b32 m0, s61
	s_barrier
	ds_read_b128 v[168:171], v150 offset:49152
	ds_read_b128 v[172:175], v150 offset:50176
	ds_read_b128 v[176:179], v150 offset:51200
	ds_read_b128 v[180:183], v150 offset:52224
	ds_read_b128 v[184:187], v150 offset:53248
	ds_read_b128 v[188:191], v150 offset:54272
	ds_read_b128 v[192:195], v150 offset:55296
	ds_read_b128 v[196:199], v150 offset:56320
	global_load_lds_dwordx4 v128, s[78:79]
	s_mov_b32 m0, s62
	s_nop 0
	global_load_lds_dwordx4 v132, s[78:79]
	s_barrier
; __device__ __forceinline__ unsigned cvt_pk_bf16(float lo, float hi) { unsigned r; asm volatile("v_cvt_pk_bf16_f32 %0, %1, %2" : "=v"(r) : "v"(lo), "v"(hi)); return r; }
; #define PG8_STAGE(bufoff, gbase, voff) do { _Pragma("unroll") for (int _i = 0; _i < 2; ++_i) \
;         __builtin_amdgcn_global_load_lds((const unsigned*)((const char*)(gbase) + (voff)[_i]), (LAS unsigned*)(lds + (bufoff) + ldsw + _i * 8192), 16, 0, 0); } while (0)
; #define PG8_MMA(ai, bj, At, Bt) do { __builtin_amdgcn_s_setprio(1); _Pragma("unroll") for (int m = 0; m < 4; ++m) _Pragma("unroll") for (int n = 0; n < 2; ++n) _Pragma("unroll") for (int k = 0; k < 2; ++k) \
;         acc[ai][bj][m][n] = __builtin_amdgcn_mfma_f32_16x16x32_bf16(Bt[n][k], At[m][k], acc[ai][bj][m][n], 0, 0, 0); __builtin_amdgcn_s_setprio(0); } while (0)
; #define PG8_WAIT_V(n) asm volatile("s_waitcnt vmcnt(" #n ")" ::: "memory")
; #define PG8_WAIT_L(n) asm volatile("s_waitcnt lgkmcnt(" #n ")" ::: "memory")
; #define PG8_BAR __builtin_amdgcn_s_barrier()
; #define PG8_SCHED __builtin_amdgcn_sched_barrier(0)
; template <class Epi, class Ptrs>
; __device__ __forceinline__ void gemm_phase(LAS unsigned char* lds, const int K, const StaticOrder& S, const Ptrs& P, const Epi& E) {
;     ...
;             PG8_BAR; PG8_WAIT_L(0); PG8_MMA(1, 0, At, B0); PG8_BAR; PG8_SCHED;
;             PG8_STAGE(PG8_SB(1, 1), b3 + hstep, voffB);
;             PG8_WAIT_V(6); PG8_BAR; PG8_MMA(1, 1, At, B1); PG8_BAR;
;         }
;     __device__ __forceinline__ void operator()(const f32x4 (&acc)[2][2][4][2], const Unit& u, int ui, int wr, int wc, int fr, int fq) const {
;         const int row0 = u.pm * 256 + wr * 64 + fr, col0 = u.pn * 256 + wc * 32 + 8 * fq;
; #pragma unroll
;         for (int ai = 0; ai < 2; ++ai)
; #pragma unroll
;             for (int m = 0; m < 4; ++m) { bf16_t* rowp = hid + (size_t)(row0 + ai * 128 + m * 16) * DFF + col0;
; #pragma unroll
;                 for (int bj = 0; bj < 2; ++bj) { f32x4 v0 = acc[ai][bj][m][0], v1 = acc[ai][bj][m][1];
; #pragma unroll
;                     for (int j = 0; j < 4; ++j) { const float a = fmaxf(v0[j], 0.f), b = fmaxf(v1[j], 0.f); v0[j] = a * a; v1[j] = b * b; }
;                     u32x4 w; w.x = cvt_pk_bf16(v0[0], v0[1]); w.y = cvt_pk_bf16(v0[2], v0[3]); w.z = cvt_pk_bf16(v1[0], v1[1]); w.w = cvt_pk_bf16(v1[2], v1[3]);
;                     *(u32x4*)(rowp + bj * 128) = w; } }
	s_waitcnt lgkmcnt(0)
	s_setprio 1
	s_waitcnt lgkmcnt(0)
	v_mfma_f32_16x16x32_bf16 v[60:63], v[152:155], v[168:171], v[60:63]
	v_mfma_f32_16x16x32_bf16 v[60:63], v[156:159], v[172:175], v[60:63]
	v_mfma_f32_16x16x32_bf16 v[56:59], v[164:167], v[172:175], v[56:59]
	v_mfma_f32_16x16x32_bf16 v[56:59], v[160:163], v[168:171], v[56:59]
	v_mfma_f32_16x16x32_bf16 v[40:43], v[160:163], v[176:179], v[40:43]
	v_mfma_f32_16x16x32_bf16 v[40:43], v[164:167], v[180:183], v[40:43]
	v_mfma_f32_16x16x32_bf16 v[44:47], v[156:159], v[180:183], v[44:47]
	v_mfma_f32_16x16x32_bf16 v[44:47], v[152:155], v[176:179], v[44:47]
	v_mfma_f32_16x16x32_bf16 v[28:31], v[152:155], v[184:187], v[28:31]
	v_mfma_f32_16x16x32_bf16 v[28:31], v[156:159], v[188:191], v[28:31]
	v_mfma_f32_16x16x32_bf16 v[24:27], v[164:167], v[188:191], v[24:27]
	v_mfma_f32_16x16x32_bf16 v[24:27], v[160:163], v[184:187], v[24:27]
	v_mfma_f32_16x16x32_bf16 v[8:11], v[160:163], v[192:195], v[8:11]
	v_mfma_f32_16x16x32_bf16 v[8:11], v[164:167], v[196:199], v[8:11]
	v_mfma_f32_16x16x32_bf16 v[12:15], v[156:159], v[196:199], v[12:15]
	v_mfma_f32_16x16x32_bf16 v[12:15], v[152:155], v[192:195], v[12:15]
	s_setprio 0
	s_barrier
	s_add_u32 s42, s42, 0x40080
	s_addc_u32 s43, s43, 0
	s_add_i32 s44, s44, s51
	s_mov_b32 m0, s44
	s_nop 0
	global_load_lds_dwordx4 v130, s[42:43]
	s_add_i32 m0, s44, 0x2000
	s_nop 0
	global_load_lds_dwordx4 v134, s[42:43]
	s_waitcnt vmcnt(6)
	s_barrier
	s_setprio 1
	v_mfma_f32_16x16x32_bf16 v[52:55], v[200:203], v[168:171], v[52:55]
	v_mfma_f32_16x16x32_bf16 v[52:55], v[204:207], v[172:175], v[52:55]
	v_mfma_f32_16x16x32_bf16 v[48:51], v[214:217], v[172:175], v[48:51]
	v_mfma_f32_16x16x32_bf16 v[48:51], v[210:213], v[168:171], v[48:51]
	v_mfma_f32_16x16x32_bf16 v[32:35], v[210:213], v[176:179], v[32:35]
	v_mfma_f32_16x16x32_bf16 v[32:35], v[214:217], v[180:183], v[32:35]
	v_mfma_f32_16x16x32_bf16 v[36:39], v[204:207], v[180:183], v[36:39]
	v_mfma_f32_16x16x32_bf16 v[36:39], v[200:203], v[176:179], v[36:39]
	v_mfma_f32_16x16x32_bf16 v[20:23], v[200:203], v[184:187], v[20:23]
	v_mfma_f32_16x16x32_bf16 v[20:23], v[204:207], v[188:191], v[20:23]
	v_mfma_f32_16x16x32_bf16 v[16:19], v[214:217], v[188:191], v[16:19]
	v_mfma_f32_16x16x32_bf16 v[16:19], v[210:213], v[184:187], v[16:19]
	v_mfma_f32_16x16x32_bf16 v[0:3], v[210:213], v[192:195], v[0:3]
	v_mfma_f32_16x16x32_bf16 v[0:3], v[214:217], v[196:199], v[0:3]
	v_mfma_f32_16x16x32_bf16 v[4:7], v[204:207], v[196:199], v[4:7]
	v_mfma_f32_16x16x32_bf16 v[4:7], v[200:203], v[192:195], v[4:7]
	s_setprio 0
	s_add_i32 s70, s70, 2
	s_add_u32 s40, s40, 0x100
	s_addc_u32 s41, s41, 0
	s_add_u32 s23, s23, 0x100
	s_addc_u32 s25, s25, 0
	s_cmp_gt_u32 s70, 13
	s_barrier
	s_cbranch_scc0 .LBB0_433
	s_nop 0
	s_nop 0
	s_nop 0
	s_nop 0
	s_nop 0
	s_nop 0
	s_nop 0
	s_nop 0
	s_nop 0
	s_nop 0
	s_nop 0
	s_nop 0
	s_nop 0
	s_nop 0
	s_nop 0
	s_nop 0
	s_nop 0
	s_nop 0
	s_nop 0
	s_nop 0
	s_nop 0
	s_nop 0
	s_nop 0
	s_nop 0
	s_nop 0
	s_nop 0
	s_nop 0
	s_nop 0
	v_lshl_add_u32 v152, s38, 8, v146
	v_max_f32_e32 v120, 0, v120
	v_ashrrev_i32_e32 v153, 31, v152
	v_max_f32_e32 v121, 0, v121
	v_max_f32_e32 v122, 0, v122
	v_lshl_or_b32 v144, s69, 8, v148
	v_lshlrev_b64 v[154:155], 13, v[152:153]
	v_mul_f32_e32 v153, v120, v120
	v_max_f32_e32 v120, 0, v125
	v_ashrrev_i32_e32 v145, 31, v144
	v_max_f32_e32 v124, 0, v124
	v_mul_f32_e32 v125, v121, v121
	v_max_f32_e32 v121, 0, v126
	v_mul_f32_e32 v126, v122, v122
	v_max_f32_e32 v122, 0, v127
	v_max_f32_e32 v123, 0, v123
	v_lshl_add_u64 v[154:155], s[10:11], 0, v[154:155]
	v_lshlrev_b64 v[156:157], 1, v[144:145]
	v_mul_f32_e32 v120, v120, v120
	v_max_f32_e32 v112, 0, v112
	v_lshl_add_u64 v[144:145], v[154:155], 0, v[156:157]
	v_mul_f32_e32 v124, v124, v124
	v_mul_f32_e32 v121, v121, v121
	v_mul_f32_e32 v122, v122, v122
	v_mul_f32_e32 v123, v123, v123
	v_cvt_pk_bf16_f32 v120, v124, v120
	v_max_f32_e32 v113, 0, v113
	v_max_f32_e32 v114, 0, v114
	v_cvt_pk_bf16_f32 v121, v121, v122
	v_cvt_pk_bf16_f32 v122, v153, v125
	v_cvt_pk_bf16_f32 v123, v126, v123
	global_store_dwordx4 v[144:145], v[120:123], off
	s_nop 1
	v_mul_f32_e32 v120, v112, v112
	v_max_f32_e32 v112, 0, v117
	v_max_f32_e32 v116, 0, v116
	v_mul_f32_e32 v117, v113, v113
	v_max_f32_e32 v113, 0, v118
	v_mul_f32_e32 v118, v114, v114
	v_max_f32_e32 v114, 0, v119
	v_max_f32_e32 v115, 0, v115
	v_mul_f32_e32 v112, v112, v112
	v_mul_f32_e32 v116, v116, v116
	v_mul_f32_e32 v113, v113, v113
	v_mul_f32_e32 v114, v114, v114
	v_mul_f32_e32 v115, v115, v115
	v_cvt_pk_bf16_f32 v112, v116, v112
	v_max_f32_e32 v104, 0, v104
	v_cvt_pk_bf16_f32 v113, v113, v114
	v_cvt_pk_bf16_f32 v114, v120, v117
	v_cvt_pk_bf16_f32 v115, v118, v115
	global_store_dwordx4 v[144:145], v[112:115], off offset:256
	s_nop 0
	v_max_f32_e32 v105, 0, v105
	v_or_b32_e32 v112, 16, v152
	v_max_f32_e32 v106, 0, v106
	v_ashrrev_i32_e32 v113, 31, v112
	v_mul_f32_e32 v114, v104, v104
	v_max_f32_e32 v104, 0, v109
	v_lshlrev_b64 v[112:113], 13, v[112:113]
	v_max_f32_e32 v108, 0, v108
	v_mul_f32_e32 v109, v105, v105
	v_max_f32_e32 v105, 0, v110
	v_mul_f32_e32 v110, v106, v106
	v_max_f32_e32 v106, 0, v111
	v_max_f32_e32 v107, 0, v107
	v_lshl_add_u64 v[112:113], s[10:11], 0, v[112:113]
	v_mul_f32_e32 v104, v104, v104
	v_max_f32_e32 v96, 0, v96
	v_lshl_add_u64 v[112:113], v[112:113], 0, v[156:157]
	v_mul_f32_e32 v108, v108, v108
	v_mul_f32_e32 v105, v105, v105
	v_mul_f32_e32 v106, v106, v106
	v_mul_f32_e32 v107, v107, v107
	v_cvt_pk_bf16_f32 v104, v108, v104
	v_max_f32_e32 v97, 0, v97
	v_max_f32_e32 v98, 0, v98
	v_cvt_pk_bf16_f32 v105, v105, v106
	v_cvt_pk_bf16_f32 v106, v114, v109
	v_cvt_pk_bf16_f32 v107, v110, v107
; __device__ __forceinline__ unsigned cvt_pk_bf16(float lo, float hi) { unsigned r; asm volatile("v_cvt_pk_bf16_f32 %0, %1, %2" : "=v"(r) : "v"(lo), "v"(hi)); return r; }
;     __device__ __forceinline__ void operator()(const f32x4 (&acc)[2][2][4][2], const Unit& u, int ui, int wr, int wc, int fr, int fq) const {
;     ...
;         for (int ai = 0; ai < 2; ++ai)
; #pragma unroll
;             for (int m = 0; m < 4; ++m) { bf16_t* rowp = hid + (size_t)(row0 + ai * 128 + m * 16) * DFF + col0;
; #pragma unroll
;                 for (int bj = 0; bj < 2; ++bj) { f32x4 v0 = acc[ai][bj][m][0], v1 = acc[ai][bj][m][1];
; #pragma unroll
;                     for (int j = 0; j < 4; ++j) { const float a = fmaxf(v0[j], 0.f), b = fmaxf(v1[j], 0.f); v0[j] = a * a; v1[j] = b * b; }
;                     u32x4 w; w.x = cvt_pk_bf16(v0[0], v0[1]); w.y = cvt_pk_bf16(v0[2], v0[3]); w.z = cvt_pk_bf16(v1[0], v1[1]); w.w = cvt_pk_bf16(v1[2], v1[3]);
;                     *(u32x4*)(rowp + bj * 128) = w; } }
	global_store_dwordx4 v[112:113], v[104:107], off
	s_nop 1
	v_mul_f32_e32 v104, v96, v96
	v_max_f32_e32 v96, 0, v101
	v_max_f32_e32 v100, 0, v100
	v_mul_f32_e32 v101, v97, v97
	v_max_f32_e32 v97, 0, v102
	v_mul_f32_e32 v102, v98, v98
	v_max_f32_e32 v98, 0, v103
	v_max_f32_e32 v99, 0, v99
	v_mul_f32_e32 v96, v96, v96
	v_mul_f32_e32 v100, v100, v100
	v_mul_f32_e32 v97, v97, v97
	v_mul_f32_e32 v98, v98, v98
	v_mul_f32_e32 v99, v99, v99
	v_cvt_pk_bf16_f32 v96, v100, v96
	v_max_f32_e32 v88, 0, v88
	v_cvt_pk_bf16_f32 v97, v97, v98
	v_cvt_pk_bf16_f32 v98, v104, v101
	v_cvt_pk_bf16_f32 v99, v102, v99
	global_store_dwordx4 v[112:113], v[96:99], off offset:256
	s_nop 0
	v_max_f32_e32 v89, 0, v89
	v_or_b32_e32 v96, 32, v152
	v_max_f32_e32 v90, 0, v90
	v_ashrrev_i32_e32 v97, 31, v96
	v_mul_f32_e32 v98, v88, v88
	v_max_f32_e32 v88, 0, v93
	v_lshlrev_b64 v[96:97], 13, v[96:97]
	v_max_f32_e32 v92, 0, v92
	v_mul_f32_e32 v93, v89, v89
	v_max_f32_e32 v89, 0, v94
	v_mul_f32_e32 v94, v90, v90
	v_max_f32_e32 v90, 0, v95
	v_max_f32_e32 v91, 0, v91
	v_lshl_add_u64 v[96:97], s[10:11], 0, v[96:97]
	v_mul_f32_e32 v88, v88, v88
	v_max_f32_e32 v80, 0, v80
	v_lshl_add_u64 v[96:97], v[96:97], 0, v[156:157]
	v_mul_f32_e32 v92, v92, v92
	v_mul_f32_e32 v89, v89, v89
	v_mul_f32_e32 v90, v90, v90
	v_mul_f32_e32 v91, v91, v91
	v_cvt_pk_bf16_f32 v88, v92, v88
	v_max_f32_e32 v81, 0, v81
	v_max_f32_e32 v82, 0, v82
	v_cvt_pk_bf16_f32 v89, v89, v90
	v_cvt_pk_bf16_f32 v90, v98, v93
	v_cvt_pk_bf16_f32 v91, v94, v91
	global_store_dwordx4 v[96:97], v[88:91], off
	s_nop 1
	v_mul_f32_e32 v88, v80, v80
	v_max_f32_e32 v80, 0, v85
	v_max_f32_e32 v84, 0, v84
	v_mul_f32_e32 v85, v81, v81
	v_max_f32_e32 v81, 0, v86
	v_mul_f32_e32 v86, v82, v82
	v_max_f32_e32 v82, 0, v87
	v_max_f32_e32 v83, 0, v83
	v_mul_f32_e32 v80, v80, v80
	v_mul_f32_e32 v84, v84, v84
	v_mul_f32_e32 v81, v81, v81
	v_mul_f32_e32 v82, v82, v82
	v_mul_f32_e32 v83, v83, v83
	v_cvt_pk_bf16_f32 v80, v84, v80
	v_max_f32_e32 v72, 0, v72
	v_cvt_pk_bf16_f32 v81, v81, v82
	v_cvt_pk_bf16_f32 v82, v88, v85
	v_cvt_pk_bf16_f32 v83, v86, v83
	global_store_dwordx4 v[96:97], v[80:83], off offset:256
	s_nop 0
	v_max_f32_e32 v73, 0, v73
	v_or_b32_e32 v80, 48, v152
	v_max_f32_e32 v74, 0, v74
	v_ashrrev_i32_e32 v81, 31, v80
	v_mul_f32_e32 v82, v72, v72
	v_max_f32_e32 v72, 0, v77
	v_lshlrev_b64 v[80:81], 13, v[80:81]
	v_max_f32_e32 v76, 0, v76
	v_mul_f32_e32 v77, v73, v73
	v_max_f32_e32 v73, 0, v78
	v_mul_f32_e32 v78, v74, v74
	v_max_f32_e32 v74, 0, v79
	v_max_f32_e32 v75, 0, v75
	v_lshl_add_u64 v[80:81], s[10:11], 0, v[80:81]
	v_mul_f32_e32 v72, v72, v72
	v_max_f32_e32 v64, 0, v64
	v_max_f32_e32 v65, 0, v65
	v_max_f32_e32 v66, 0, v66
	v_lshl_add_u64 v[80:81], v[80:81], 0, v[156:157]
	v_mul_f32_e32 v76, v76, v76
	v_mul_f32_e32 v73, v73, v73
	v_mul_f32_e32 v74, v74, v74
	v_mul_f32_e32 v75, v75, v75
	v_cvt_pk_bf16_f32 v72, v76, v72
	v_cvt_pk_bf16_f32 v73, v73, v74
	v_cvt_pk_bf16_f32 v74, v82, v77
	v_cvt_pk_bf16_f32 v75, v78, v75
	global_store_dwordx4 v[80:81], v[72:75], off
	v_max_f32_e32 v68, 0, v68
	v_max_f32_e32 v67, 0, v67
	v_mul_f32_e32 v72, v64, v64
	v_max_f32_e32 v64, 0, v69
	v_mul_f32_e32 v69, v65, v65
	v_max_f32_e32 v65, 0, v70
	v_mul_f32_e32 v70, v66, v66
	v_max_f32_e32 v66, 0, v71
	v_mul_f32_e32 v64, v64, v64
	v_mul_f32_e32 v65, v65, v65
	v_mul_f32_e32 v66, v66, v66
	v_max_f32_e32 v56, 0, v56
	v_mul_f32_e32 v68, v68, v68
	v_mul_f32_e32 v67, v67, v67
	v_cvt_pk_bf16_f32 v64, v68, v64
	v_cvt_pk_bf16_f32 v65, v65, v66
	v_cvt_pk_bf16_f32 v66, v72, v69
	v_max_f32_e32 v57, 0, v57
	v_max_f32_e32 v58, 0, v58
	v_cvt_pk_bf16_f32 v67, v70, v67
	global_store_dwordx4 v[80:81], v[64:67], off offset:256
	s_nop 0
	v_max_f32_e32 v60, 0, v60
	v_mul_f32_e32 v66, v56, v56
	v_max_f32_e32 v56, 0, v61
	v_mul_f32_e32 v61, v57, v57
	v_max_f32_e32 v57, 0, v62
	v_mul_f32_e32 v62, v58, v58
	v_max_f32_e32 v58, 0, v63
	v_mul_f32_e32 v60, v60, v60
	v_mul_f32_e32 v56, v56, v56
	v_max_f32_e32 v59, 0, v59
	v_mul_f32_e32 v57, v57, v57
	v_mul_f32_e32 v58, v58, v58
	v_cvt_pk_bf16_f32 v56, v60, v56
	v_add_co_u32_e32 v60, vcc, s65, v144
	v_max_f32_e32 v48, 0, v48
	v_max_f32_e32 v49, 0, v49
	v_max_f32_e32 v50, 0, v50
	v_mul_f32_e32 v59, v59, v59
	v_cvt_pk_bf16_f32 v57, v57, v58
	v_cvt_pk_bf16_f32 v58, v66, v61
	v_addc_co_u32_e32 v61, vcc, 0, v145, vcc
	v_cvt_pk_bf16_f32 v59, v62, v59
	global_store_dwordx4 v[60:61], v[56:59], off
	v_max_f32_e32 v52, 0, v52
	v_max_f32_e32 v51, 0, v51
	v_mul_f32_e32 v56, v48, v48
	v_max_f32_e32 v48, 0, v53
	v_mul_f32_e32 v53, v49, v49
	v_max_f32_e32 v49, 0, v54
	v_mul_f32_e32 v54, v50, v50
	v_max_f32_e32 v50, 0, v55
	v_mul_f32_e32 v48, v48, v48
	v_mul_f32_e32 v49, v49, v49
	v_mul_f32_e32 v50, v50, v50
; __device__ __forceinline__ unsigned cvt_pk_bf16(float lo, float hi) { unsigned r; asm volatile("v_cvt_pk_bf16_f32 %0, %1, %2" : "=v"(r) : "v"(lo), "v"(hi)); return r; }
; #define PG8_WAIT_V(n) asm volatile("s_waitcnt vmcnt(" #n ")" ::: "memory")
; #define PG8_BAR __builtin_amdgcn_s_barrier()
; template <class Epi, class Ptrs>
; __device__ __forceinline__ void gemm_phase(LAS unsigned char* lds, const int K, const StaticOrder& S, const Ptrs& P, const Epi& E) {
;     ...
;     PG8_WAIT_V(0);
;     if (wr == 0) PG8_BAR;
;     PG8_BAR;
;     __device__ __forceinline__ void operator()(const f32x4 (&acc)[2][2][4][2], const Unit& u, int ui, int wr, int wc, int fr, int fq) const {
;         const int row0 = u.pm * 256 + wr * 64 + fr, col0 = u.pn * 256 + wc * 32 + 8 * fq;
; #pragma unroll
;         for (int ai = 0; ai < 2; ++ai)
; #pragma unroll
;             for (int m = 0; m < 4; ++m) { bf16_t* rowp = hid + (size_t)(row0 + ai * 128 + m * 16) * DFF + col0;
; #pragma unroll
;                 for (int bj = 0; bj < 2; ++bj) { f32x4 v0 = acc[ai][bj][m][0], v1 = acc[ai][bj][m][1];
; #pragma unroll
;                     for (int j = 0; j < 4; ++j) { const float a = fmaxf(v0[j], 0.f), b = fmaxf(v1[j], 0.f); v0[j] = a * a; v1[j] = b * b; }
;                     u32x4 w; w.x = cvt_pk_bf16(v0[0], v0[1]); w.y = cvt_pk_bf16(v0[2], v0[3]); w.z = cvt_pk_bf16(v1[0], v1[1]); w.w = cvt_pk_bf16(v1[2], v1[3]);
;                     *(u32x4*)(rowp + bj * 128) = w; } }
;     }
	v_max_f32_e32 v40, 0, v40
	v_lshl_add_u64 v[64:65], v[144:145], 0, s[14:15]
	v_mul_f32_e32 v52, v52, v52
	v_mul_f32_e32 v51, v51, v51
	v_cvt_pk_bf16_f32 v48, v52, v48
	v_cvt_pk_bf16_f32 v49, v49, v50
	v_cvt_pk_bf16_f32 v50, v56, v53
	v_max_f32_e32 v41, 0, v41
	v_max_f32_e32 v42, 0, v42
	v_cvt_pk_bf16_f32 v51, v54, v51
	global_store_dwordx4 v[64:65], v[48:51], off offset:256
	s_nop 0
	v_max_f32_e32 v44, 0, v44
	v_mul_f32_e32 v50, v40, v40
	v_max_f32_e32 v40, 0, v45
	v_mul_f32_e32 v45, v41, v41
	v_max_f32_e32 v41, 0, v46
	v_mul_f32_e32 v46, v42, v42
	v_max_f32_e32 v42, 0, v47
	v_mul_f32_e32 v44, v44, v44
	v_mul_f32_e32 v40, v40, v40
	v_max_f32_e32 v43, 0, v43
	v_mul_f32_e32 v41, v41, v41
	v_mul_f32_e32 v42, v42, v42
	v_cvt_pk_bf16_f32 v40, v44, v40
	v_add_co_u32_e32 v44, vcc, s66, v144
	v_max_f32_e32 v32, 0, v32
	v_max_f32_e32 v33, 0, v33
	v_max_f32_e32 v34, 0, v34
	v_mul_f32_e32 v43, v43, v43
	v_cvt_pk_bf16_f32 v41, v41, v42
	v_cvt_pk_bf16_f32 v42, v50, v45
	v_addc_co_u32_e32 v45, vcc, 0, v145, vcc
	v_cvt_pk_bf16_f32 v43, v46, v43
	global_store_dwordx4 v[44:45], v[40:43], off
	v_max_f32_e32 v36, 0, v36
	v_max_f32_e32 v35, 0, v35
	v_mul_f32_e32 v40, v32, v32
	v_max_f32_e32 v32, 0, v37
	v_mul_f32_e32 v37, v33, v33
	v_max_f32_e32 v33, 0, v38
	v_mul_f32_e32 v38, v34, v34
	v_max_f32_e32 v34, 0, v39
	v_mul_f32_e32 v32, v32, v32
	v_mul_f32_e32 v33, v33, v33
	v_mul_f32_e32 v34, v34, v34
	v_max_f32_e32 v24, 0, v24
	v_lshl_add_u64 v[48:49], v[144:145], 0, s[16:17]
	v_mul_f32_e32 v36, v36, v36
	v_mul_f32_e32 v35, v35, v35
	v_cvt_pk_bf16_f32 v32, v36, v32
	v_cvt_pk_bf16_f32 v33, v33, v34
	v_cvt_pk_bf16_f32 v34, v40, v37
	v_max_f32_e32 v25, 0, v25
	v_max_f32_e32 v26, 0, v26
	v_cvt_pk_bf16_f32 v35, v38, v35
	global_store_dwordx4 v[48:49], v[32:35], off offset:256
	s_nop 0
	v_max_f32_e32 v28, 0, v28
	v_mul_f32_e32 v34, v24, v24
	v_max_f32_e32 v24, 0, v29
	v_mul_f32_e32 v29, v25, v25
	v_max_f32_e32 v25, 0, v30
	v_mul_f32_e32 v30, v26, v26
	v_max_f32_e32 v26, 0, v31
	v_mul_f32_e32 v28, v28, v28
	v_mul_f32_e32 v24, v24, v24
	v_max_f32_e32 v27, 0, v27
	v_mul_f32_e32 v25, v25, v25
	v_mul_f32_e32 v26, v26, v26
	v_cvt_pk_bf16_f32 v24, v28, v24
	v_add_co_u32_e32 v28, vcc, s67, v144
	v_max_f32_e32 v16, 0, v16
	v_max_f32_e32 v17, 0, v17
	v_max_f32_e32 v18, 0, v18
	v_mul_f32_e32 v27, v27, v27
	v_cvt_pk_bf16_f32 v25, v25, v26
	v_cvt_pk_bf16_f32 v26, v34, v29
	v_addc_co_u32_e32 v29, vcc, 0, v145, vcc
	v_cvt_pk_bf16_f32 v27, v30, v27
	global_store_dwordx4 v[28:29], v[24:27], off
	v_max_f32_e32 v20, 0, v20
	v_max_f32_e32 v19, 0, v19
	v_mul_f32_e32 v24, v16, v16
	v_max_f32_e32 v16, 0, v21
	v_mul_f32_e32 v21, v17, v17
	v_max_f32_e32 v17, 0, v22
	v_mul_f32_e32 v22, v18, v18
	v_max_f32_e32 v18, 0, v23
	v_mul_f32_e32 v16, v16, v16
	v_mul_f32_e32 v17, v17, v17
	v_mul_f32_e32 v18, v18, v18
	v_max_f32_e32 v8, 0, v8
	v_lshl_add_u64 v[32:33], v[144:145], 0, s[18:19]
	v_mul_f32_e32 v20, v20, v20
	v_mul_f32_e32 v19, v19, v19
	v_cvt_pk_bf16_f32 v16, v20, v16
	v_cvt_pk_bf16_f32 v17, v17, v18
	v_cvt_pk_bf16_f32 v18, v24, v21
	v_max_f32_e32 v9, 0, v9
	v_max_f32_e32 v10, 0, v10
	v_cvt_pk_bf16_f32 v19, v22, v19
	global_store_dwordx4 v[32:33], v[16:19], off offset:256
	s_nop 0
	v_max_f32_e32 v12, 0, v12
	v_mul_f32_e32 v18, v8, v8
	v_max_f32_e32 v8, 0, v13
	v_mul_f32_e32 v13, v9, v9
	v_max_f32_e32 v9, 0, v14
	v_mul_f32_e32 v14, v10, v10
	v_max_f32_e32 v10, 0, v15
	v_mul_f32_e32 v12, v12, v12
	v_mul_f32_e32 v8, v8, v8
	v_max_f32_e32 v11, 0, v11
	v_mul_f32_e32 v9, v9, v9
	v_mul_f32_e32 v10, v10, v10
	v_cvt_pk_bf16_f32 v8, v12, v8
	v_add_co_u32_e32 v12, vcc, s68, v144
	v_max_f32_e32 v0, 0, v0
	v_max_f32_e32 v1, 0, v1
	v_max_f32_e32 v2, 0, v2
	v_mul_f32_e32 v11, v11, v11
	v_cvt_pk_bf16_f32 v9, v9, v10
	v_cvt_pk_bf16_f32 v10, v18, v13
	v_addc_co_u32_e32 v13, vcc, 0, v145, vcc
	v_cvt_pk_bf16_f32 v11, v14, v11
	global_store_dwordx4 v[12:13], v[8:11], off
	v_max_f32_e32 v3, 0, v3
	v_max_f32_e32 v4, 0, v4
	v_mul_f32_e32 v8, v0, v0
	v_max_f32_e32 v0, 0, v5
	v_mul_f32_e32 v5, v1, v1
	v_max_f32_e32 v1, 0, v6
	v_mul_f32_e32 v6, v2, v2
	v_max_f32_e32 v2, 0, v7
	v_lshl_add_u64 v[16:17], v[144:145], 0, s[20:21]
	v_mul_f32_e32 v0, v0, v0
	v_mul_f32_e32 v1, v1, v1
	v_mul_f32_e32 v2, v2, v2
	v_mul_f32_e32 v3, v3, v3
	s_and_b64 vcc, exec, s[4:5]
	s_mov_b32 s69, s22
	s_mov_b32 s38, s24
	s_mov_b64 s[40:41], s[0:1]
	s_mov_b64 s[42:43], s[36:37]
	v_mul_f32_e32 v4, v4, v4
	v_cvt_pk_bf16_f32 v0, v4, v0
	v_cvt_pk_bf16_f32 v1, v1, v2
	v_cvt_pk_bf16_f32 v2, v8, v5
	v_cvt_pk_bf16_f32 v3, v6, v3
	global_store_dwordx4 v[16:17], v[0:3], off offset:256
	s_cbranch_vccz .LBB0_428
	s_waitcnt vmcnt(0)
	s_cmpk_gt_u32 s46, 0xff
	s_cbranch_scc1 .LBB0_437
	s_barrier

; #define PG8_STAGE(bufoff, gbase, voff) do { _Pragma("unroll") for (int _i = 0; _i < 2; ++_i) \
;         __builtin_amdgcn_global_load_lds((const unsigned*)((const char*)(gbase) + (voff)[_i]), (LAS unsigned*)(lds + (bufoff) + ldsw + _i * 8192), 16, 0, 0); } while (0)
; #define PG8_LDA(dst, b, h) do { _Pragma("unroll") for (int m = 0; m < 4; ++m) _Pragma("unroll") for (int k = 0; k < 2; ++k) dst[m][k] = *(const LAS bf16x8*)(lds + PG8_SA(b, h) + aoff + m * 2048 + k * 1024); } while (0)
; #define PG8_LDB(dst, b, h) do { _Pragma("unroll") for (int n = 0; n < 2; ++n) _Pragma("unroll") for (int k = 0; k < 2; ++k) dst[n][k] = *(const LAS bf16x8*)(lds + PG8_SB(b, h) + boff + n * 2048 + k * 1024); } while (0)
; #define PG8_MMA(ai, bj, At, Bt) do { __builtin_amdgcn_s_setprio(1); _Pragma("unroll") for (int m = 0; m < 4; ++m) _Pragma("unroll") for (int n = 0; n < 2; ++n) _Pragma("unroll") for (int k = 0; k < 2; ++k) \
;         acc[ai][bj][m][n] = __builtin_amdgcn_mfma_f32_16x16x32_bf16(Bt[n][k], At[m][k], acc[ai][bj][m][n], 0, 0, 0); __builtin_amdgcn_s_setprio(0); } while (0)
; #define PG8_WAIT_V(n) asm volatile("s_waitcnt vmcnt(" #n ")" ::: "memory")
; #define PG8_WAIT_L(n) asm volatile("s_waitcnt lgkmcnt(" #n ")" ::: "memory")
; template <class Epi, class Ptrs>
; __device__ __forceinline__ void gemm_phase(LAS unsigned char* lds, const int K, const StaticOrder& S, const Ptrs& P, const Epi& E) {
;     ...
;         for (int t = 0; t < nt; t += 2) {
;             const bool last = (t == nt - 2);
;             const char* a1 = cA + (size_t)(t + 1) * kstep;
;             const char* a2 = last ? nA : cA + (size_t)(t + 2) * kstep; const char* b2 = last ? nB : cB + (size_t)(t + 2) * kstep;
;             const char* a3 = a2 + kstep; const char* b3 = b2 + kstep;
;             PG8_LDB(B0, 0, 0); PG8_SCHED; PG8_LDA(At, 0, 0); PG8_STAGE(PG8_SA(1, 1), a1 + hstep, voffA);
;             PG8_WAIT_L(8); PG8_BAR; PG8_WAIT_L(0); PG8_MMA(0, 0, At, B0); PG8_BAR; PG8_SCHED;
;             PG8_LDB(B1, 0, 1); PG8_STAGE(PG8_SB(0, 0), b2, voffB);
;             PG8_BAR; PG8_WAIT_L(0); PG8_MMA(0, 1, At, B1); PG8_BAR;
;             PG8_LDA(At, 0, 1); PG8_STAGE(PG8_SA(0, 0), a2, voffA);
;             PG8_BAR; PG8_WAIT_L(0); PG8_MMA(1, 0, At, B0); PG8_BAR; PG8_SCHED;
;             PG8_STAGE(PG8_SB(0, 1), b2 + hstep, voffB);
;             PG8_WAIT_V(6); PG8_BAR; PG8_MMA(1, 1, At, B1); PG8_BAR;
.LBB0_522:
	ds_read_b128 v[128:131], v193
	ds_read_b128 v[132:135], v193 offset:1024
	ds_read_b128 v[136:139], v193 offset:2048
	ds_read_b128 v[140:143], v193 offset:3072
	s_add_u32 s22, s20, 0xfff00080
	s_addc_u32 s23, s21, -1
	s_cmp_eq_u32 s46, 60
	s_cselect_b32 s25, s5, s23
	s_cselect_b32 s24, s4, s22
	s_cselect_b32 s23, s15, s13
	s_cselect_b32 s22, s14, s11
	s_add_i32 m0, s17, 0xc000
	ds_read_b128 v[144:147], v194
	ds_read_b128 v[148:151], v194 offset:1024
	ds_read_b128 v[152:155], v194 offset:2048
	ds_read_b128 v[156:159], v194 offset:3072
	ds_read_b128 v[176:179], v194 offset:4096
	ds_read_b128 v[180:183], v194 offset:5120
	ds_read_b128 v[196:199], v194 offset:6144
	ds_read_b128 v[200:203], v194 offset:7168
	global_load_lds_dwordx4 v168, s[20:21]
	s_add_i32 m0, s17, 0xe000
	s_nop 0
	global_load_lds_dwordx4 v170, s[20:21]
	s_waitcnt lgkmcnt(8)
	s_barrier
	s_waitcnt lgkmcnt(0)
	s_setprio 1
	s_waitcnt lgkmcnt(0)
	v_mfma_f32_16x16x32_bf16 v[124:127], v[128:131], v[144:147], v[124:127]
	v_mfma_f32_16x16x32_bf16 v[124:127], v[132:135], v[148:151], v[124:127]
	v_mfma_f32_16x16x32_bf16 v[120:123], v[140:143], v[148:151], v[120:123]
	v_mfma_f32_16x16x32_bf16 v[120:123], v[136:139], v[144:147], v[120:123]
	v_mfma_f32_16x16x32_bf16 v[104:107], v[136:139], v[152:155], v[104:107]
	v_mfma_f32_16x16x32_bf16 v[104:107], v[140:143], v[156:159], v[104:107]
	v_mfma_f32_16x16x32_bf16 v[112:115], v[132:135], v[156:159], v[112:115]
	v_mfma_f32_16x16x32_bf16 v[112:115], v[128:131], v[152:155], v[112:115]
	v_mfma_f32_16x16x32_bf16 v[92:95], v[128:131], v[176:179], v[92:95]
	v_mfma_f32_16x16x32_bf16 v[92:95], v[132:135], v[180:183], v[92:95]
	v_mfma_f32_16x16x32_bf16 v[88:91], v[140:143], v[180:183], v[88:91]
	v_mfma_f32_16x16x32_bf16 v[88:91], v[136:139], v[176:179], v[88:91]
	v_mfma_f32_16x16x32_bf16 v[72:75], v[136:139], v[196:199], v[72:75]
	v_mfma_f32_16x16x32_bf16 v[72:75], v[140:143], v[200:203], v[72:75]
	v_mfma_f32_16x16x32_bf16 v[76:79], v[132:135], v[200:203], v[76:79]
	v_mfma_f32_16x16x32_bf16 v[76:79], v[128:131], v[196:199], v[76:79]
	s_setprio 0
	s_barrier
	s_add_i32 s47, s42, s34
	s_add_u32 s90, s22, 0x80
	s_addc_u32 s91, s23, 0
	s_mov_b32 m0, s47
	ds_read_b128 v[204:207], v195
	ds_read_b128 v[208:211], v195 offset:1024
	ds_read_b128 v[212:215], v195 offset:2048
	ds_read_b128 v[216:219], v195 offset:3072
	global_load_lds_dwordx4 v162, s[22:23]
	s_add_i32 m0, s47, 0x2000
	s_nop 0
	global_load_lds_dwordx4 v166, s[22:23]
	s_barrier
	s_waitcnt lgkmcnt(0)
	s_setprio 1
	s_waitcnt lgkmcnt(0)
	v_mfma_f32_16x16x32_bf16 v[116:119], v[204:207], v[144:147], v[116:119]
	v_mfma_f32_16x16x32_bf16 v[116:119], v[208:211], v[148:151], v[116:119]
	v_mfma_f32_16x16x32_bf16 v[108:111], v[216:219], v[148:151], v[108:111]
	v_mfma_f32_16x16x32_bf16 v[108:111], v[212:215], v[144:147], v[108:111]
	v_mfma_f32_16x16x32_bf16 v[96:99], v[212:215], v[152:155], v[96:99]
	v_mfma_f32_16x16x32_bf16 v[96:99], v[216:219], v[156:159], v[96:99]
	v_mfma_f32_16x16x32_bf16 v[100:103], v[208:211], v[156:159], v[100:103]
	v_mfma_f32_16x16x32_bf16 v[100:103], v[204:207], v[152:155], v[100:103]
	v_mfma_f32_16x16x32_bf16 v[84:87], v[204:207], v[176:179], v[84:87]
	v_mfma_f32_16x16x32_bf16 v[84:87], v[208:211], v[180:183], v[84:87]
	v_mfma_f32_16x16x32_bf16 v[80:83], v[216:219], v[180:183], v[80:83]
	v_mfma_f32_16x16x32_bf16 v[80:83], v[212:215], v[176:179], v[80:83]
	v_mfma_f32_16x16x32_bf16 v[64:67], v[212:215], v[196:199], v[64:67]
	v_mfma_f32_16x16x32_bf16 v[64:67], v[216:219], v[200:203], v[64:67]
	v_mfma_f32_16x16x32_bf16 v[68:71], v[208:211], v[200:203], v[68:71]
	v_mfma_f32_16x16x32_bf16 v[68:71], v[204:207], v[196:199], v[68:71]
	s_setprio 0
	s_mov_b32 m0, s17
	s_add_u32 s92, s24, 0x80
	s_addc_u32 s93, s25, 0
	s_barrier
	ds_read_b128 v[144:147], v194 offset:16384
	ds_read_b128 v[148:151], v194 offset:17408
	ds_read_b128 v[152:155], v194 offset:18432
	ds_read_b128 v[156:159], v194 offset:19456
	ds_read_b128 v[176:179], v194 offset:20480
	ds_read_b128 v[180:183], v194 offset:21504
	ds_read_b128 v[196:199], v194 offset:22528
	ds_read_b128 v[200:203], v194 offset:23552
	global_load_lds_dwordx4 v160, s[24:25]
	s_mov_b32 m0, s19
	s_nop 0
	global_load_lds_dwordx4 v164, s[24:25]
	s_barrier
	s_waitcnt lgkmcnt(0)
	s_setprio 1
	s_waitcnt lgkmcnt(0)
	v_mfma_f32_16x16x32_bf16 v[60:63], v[128:131], v[144:147], v[60:63]
	v_mfma_f32_16x16x32_bf16 v[60:63], v[132:135], v[148:151], v[60:63]
	v_mfma_f32_16x16x32_bf16 v[56:59], v[140:143], v[148:151], v[56:59]
	v_mfma_f32_16x16x32_bf16 v[56:59], v[136:139], v[144:147], v[56:59]
	v_mfma_f32_16x16x32_bf16 v[40:43], v[136:139], v[152:155], v[40:43]
	v_mfma_f32_16x16x32_bf16 v[40:43], v[140:143], v[156:159], v[40:43]
	v_mfma_f32_16x16x32_bf16 v[48:51], v[132:135], v[156:159], v[48:51]
	v_mfma_f32_16x16x32_bf16 v[48:51], v[128:131], v[152:155], v[48:51]
	v_mfma_f32_16x16x32_bf16 v[32:35], v[128:131], v[176:179], v[32:35]
	v_mfma_f32_16x16x32_bf16 v[32:35], v[132:135], v[180:183], v[32:35]
	v_mfma_f32_16x16x32_bf16 v[24:27], v[140:143], v[180:183], v[24:27]
	v_mfma_f32_16x16x32_bf16 v[24:27], v[136:139], v[176:179], v[24:27]
	v_mfma_f32_16x16x32_bf16 v[8:11], v[136:139], v[196:199], v[8:11]
	v_mfma_f32_16x16x32_bf16 v[8:11], v[140:143], v[200:203], v[8:11]
	v_mfma_f32_16x16x32_bf16 v[16:19], v[132:135], v[200:203], v[16:19]
	v_mfma_f32_16x16x32_bf16 v[16:19], v[128:131], v[196:199], v[16:19]
	s_setprio 0
	s_barrier
	s_add_u32 s48, s22, 0x100000
	s_addc_u32 s49, s23, 0
	s_add_i32 s47, s43, s34
	s_mov_b32 m0, s47
	s_nop 0
	global_load_lds_dwordx4 v162, s[48:49]
	s_add_i32 m0, s47, 0x2000
	s_nop 0
	global_load_lds_dwordx4 v166, s[48:49]
	s_waitcnt vmcnt(6)
	s_barrier
; #define PG8_STAGE(bufoff, gbase, voff) do { _Pragma("unroll") for (int _i = 0; _i < 2; ++_i) \
;         __builtin_amdgcn_global_load_lds((const unsigned*)((const char*)(gbase) + (voff)[_i]), (LAS unsigned*)(lds + (bufoff) + ldsw + _i * 8192), 16, 0, 0); } while (0)
; #define PG8_LDA(dst, b, h) do { _Pragma("unroll") for (int m = 0; m < 4; ++m) _Pragma("unroll") for (int k = 0; k < 2; ++k) dst[m][k] = *(const LAS bf16x8*)(lds + PG8_SA(b, h) + aoff + m * 2048 + k * 1024); } while (0)
; #define PG8_LDB(dst, b, h) do { _Pragma("unroll") for (int n = 0; n < 2; ++n) _Pragma("unroll") for (int k = 0; k < 2; ++k) dst[n][k] = *(const LAS bf16x8*)(lds + PG8_SB(b, h) + boff + n * 2048 + k * 1024); } while (0)
; #define PG8_MMA(ai, bj, At, Bt) do { __builtin_amdgcn_s_setprio(1); _Pragma("unroll") for (int m = 0; m < 4; ++m) _Pragma("unroll") for (int n = 0; n < 2; ++n) _Pragma("unroll") for (int k = 0; k < 2; ++k) \
;         acc[ai][bj][m][n] = __builtin_amdgcn_mfma_f32_16x16x32_bf16(Bt[n][k], At[m][k], acc[ai][bj][m][n], 0, 0, 0); __builtin_amdgcn_s_setprio(0); } while (0)
; #define PG8_WAIT_V(n) asm volatile("s_waitcnt vmcnt(" #n ")" ::: "memory")
; #define PG8_WAIT_L(n) asm volatile("s_waitcnt lgkmcnt(" #n ")" ::: "memory")
; #define PG8_BAR __builtin_amdgcn_s_barrier()
; #define PG8_SCHED __builtin_amdgcn_sched_barrier(0)
; template <class Epi, class Ptrs>
; __device__ __forceinline__ void gemm_phase(LAS unsigned char* lds, const int K, const StaticOrder& S, const Ptrs& P, const Epi& E) {
;     ...
;             PG8_WAIT_V(6); PG8_BAR; PG8_MMA(1, 1, At, B1); PG8_BAR;
;             PG8_LDB(B0, 1, 0); PG8_SCHED; PG8_LDA(At, 1, 0); PG8_STAGE(PG8_SA(0, 1), a2 + hstep, voffA);
;             PG8_WAIT_L(8); PG8_BAR; PG8_WAIT_L(0); PG8_MMA(0, 0, At, B0); PG8_BAR; PG8_SCHED;
;             PG8_LDB(B1, 1, 1); PG8_STAGE(PG8_SB(1, 0), b3, voffB);
;             PG8_BAR; PG8_WAIT_L(0); PG8_MMA(0, 1, At, B1); PG8_BAR;
;             PG8_LDA(At, 1, 1); PG8_STAGE(PG8_SA(1, 0), a3, voffA);
;             PG8_BAR; PG8_WAIT_L(0); PG8_MMA(1, 0, At, B0); PG8_BAR; PG8_SCHED;
	s_setprio 1
	v_mfma_f32_16x16x32_bf16 v[52:55], v[204:207], v[144:147], v[52:55]
	v_mfma_f32_16x16x32_bf16 v[52:55], v[208:211], v[148:151], v[52:55]
	v_mfma_f32_16x16x32_bf16 v[44:47], v[216:219], v[148:151], v[44:47]
	v_mfma_f32_16x16x32_bf16 v[44:47], v[212:215], v[144:147], v[44:47]
	v_mfma_f32_16x16x32_bf16 v[28:31], v[212:215], v[152:155], v[28:31]
	v_mfma_f32_16x16x32_bf16 v[28:31], v[216:219], v[156:159], v[28:31]
	v_mfma_f32_16x16x32_bf16 v[36:39], v[208:211], v[156:159], v[36:39]
	v_mfma_f32_16x16x32_bf16 v[36:39], v[204:207], v[152:155], v[36:39]
	v_mfma_f32_16x16x32_bf16 v[20:23], v[204:207], v[176:179], v[20:23]
	v_mfma_f32_16x16x32_bf16 v[20:23], v[208:211], v[180:183], v[20:23]
	v_mfma_f32_16x16x32_bf16 v[12:15], v[216:219], v[180:183], v[12:15]
	v_mfma_f32_16x16x32_bf16 v[12:15], v[212:215], v[176:179], v[12:15]
	v_mfma_f32_16x16x32_bf16 v[0:3], v[212:215], v[196:199], v[0:3]
	v_mfma_f32_16x16x32_bf16 v[0:3], v[216:219], v[200:203], v[0:3]
	v_mfma_f32_16x16x32_bf16 v[4:7], v[208:211], v[200:203], v[4:7]
	v_mfma_f32_16x16x32_bf16 v[4:7], v[204:207], v[196:199], v[4:7]
	s_setprio 0
	s_add_i32 s47, 0, 0x18000
	s_barrier
	ds_read_b128 v[128:131], v252
	ds_read_b128 v[132:135], v252 offset:1024
	ds_read_b128 v[136:139], v252 offset:2048
	ds_read_b128 v[140:143], v252 offset:3072
	s_add_u32 s24, s24, 0x100000
	s_addc_u32 s25, s25, 0
	s_mov_b32 m0, s40
	ds_read_b128 v[144:147], v194 offset:32768
	ds_read_b128 v[148:151], v194 offset:33792
	ds_read_b128 v[152:155], v194 offset:34816
	ds_read_b128 v[156:159], v194 offset:35840
	ds_read_b128 v[176:179], v194 offset:36864
	ds_read_b128 v[180:183], v194 offset:37888
	ds_read_b128 v[196:199], v194 offset:38912
	ds_read_b128 v[200:203], v194 offset:39936
	global_load_lds_dwordx4 v160, s[24:25]
	s_mov_b32 m0, s41
	s_nop 0
	global_load_lds_dwordx4 v164, s[24:25]
	s_waitcnt lgkmcnt(8)
	s_barrier
	s_waitcnt lgkmcnt(0)
	s_setprio 1
	s_waitcnt lgkmcnt(0)
	v_mfma_f32_16x16x32_bf16 v[124:127], v[128:131], v[144:147], v[124:127]
	v_mfma_f32_16x16x32_bf16 v[124:127], v[132:135], v[148:151], v[124:127]
	v_mfma_f32_16x16x32_bf16 v[120:123], v[140:143], v[148:151], v[120:123]
	v_mfma_f32_16x16x32_bf16 v[120:123], v[136:139], v[144:147], v[120:123]
	v_mfma_f32_16x16x32_bf16 v[104:107], v[136:139], v[152:155], v[104:107]
	v_mfma_f32_16x16x32_bf16 v[104:107], v[140:143], v[156:159], v[104:107]
	v_mfma_f32_16x16x32_bf16 v[112:115], v[132:135], v[156:159], v[112:115]
	v_mfma_f32_16x16x32_bf16 v[112:115], v[128:131], v[152:155], v[112:115]
	v_mfma_f32_16x16x32_bf16 v[92:95], v[128:131], v[176:179], v[92:95]
	v_mfma_f32_16x16x32_bf16 v[92:95], v[132:135], v[180:183], v[92:95]
	v_mfma_f32_16x16x32_bf16 v[88:91], v[140:143], v[180:183], v[88:91]
	v_mfma_f32_16x16x32_bf16 v[88:91], v[136:139], v[176:179], v[88:91]
	v_mfma_f32_16x16x32_bf16 v[72:75], v[136:139], v[196:199], v[72:75]
	v_mfma_f32_16x16x32_bf16 v[72:75], v[140:143], v[200:203], v[72:75]
	v_mfma_f32_16x16x32_bf16 v[76:79], v[132:135], v[200:203], v[76:79]
	v_mfma_f32_16x16x32_bf16 v[76:79], v[128:131], v[196:199], v[76:79]
	s_setprio 0
	s_barrier
	s_add_i32 s24, 0, 0x1c000
	s_add_i32 s25, s47, s34
	s_mov_b32 m0, s25
	ds_read_b128 v[204:207], v253
	ds_read_b128 v[208:211], v253 offset:1024
	ds_read_b128 v[212:215], v253 offset:2048
	ds_read_b128 v[216:219], v253 offset:3072
	global_load_lds_dwordx4 v162, s[90:91]
	s_add_i32 m0, s25, 0x2000
	s_nop 0
	global_load_lds_dwordx4 v166, s[90:91]
	s_barrier
	s_waitcnt lgkmcnt(0)
	s_setprio 1
	s_waitcnt lgkmcnt(0)
	v_mfma_f32_16x16x32_bf16 v[116:119], v[204:207], v[144:147], v[116:119]
	v_mfma_f32_16x16x32_bf16 v[116:119], v[208:211], v[148:151], v[116:119]
	v_mfma_f32_16x16x32_bf16 v[108:111], v[216:219], v[148:151], v[108:111]
	v_mfma_f32_16x16x32_bf16 v[108:111], v[212:215], v[144:147], v[108:111]
	v_mfma_f32_16x16x32_bf16 v[96:99], v[212:215], v[152:155], v[96:99]
	v_mfma_f32_16x16x32_bf16 v[96:99], v[216:219], v[156:159], v[96:99]
	v_mfma_f32_16x16x32_bf16 v[100:103], v[208:211], v[156:159], v[100:103]
	v_mfma_f32_16x16x32_bf16 v[100:103], v[204:207], v[152:155], v[100:103]
	v_mfma_f32_16x16x32_bf16 v[84:87], v[204:207], v[176:179], v[84:87]
	v_mfma_f32_16x16x32_bf16 v[84:87], v[208:211], v[180:183], v[84:87]
	v_mfma_f32_16x16x32_bf16 v[80:83], v[216:219], v[180:183], v[80:83]
	v_mfma_f32_16x16x32_bf16 v[80:83], v[212:215], v[176:179], v[80:83]
	v_mfma_f32_16x16x32_bf16 v[64:67], v[212:215], v[196:199], v[64:67]
	v_mfma_f32_16x16x32_bf16 v[64:67], v[216:219], v[200:203], v[64:67]
	v_mfma_f32_16x16x32_bf16 v[68:71], v[208:211], v[200:203], v[68:71]
	v_mfma_f32_16x16x32_bf16 v[68:71], v[204:207], v[196:199], v[68:71]
	s_setprio 0
	s_mov_b32 m0, s28
	s_barrier
	ds_read_b128 v[144:147], v194 offset:49152
	ds_read_b128 v[148:151], v194 offset:50176
	ds_read_b128 v[152:155], v194 offset:51200
	ds_read_b128 v[156:159], v194 offset:52224
	ds_read_b128 v[176:179], v194 offset:53248
	ds_read_b128 v[180:183], v194 offset:54272
	ds_read_b128 v[196:199], v194 offset:55296
	ds_read_b128 v[200:203], v194 offset:56320
	global_load_lds_dwordx4 v160, s[92:93]
	s_mov_b32 m0, s29
	s_nop 0
	global_load_lds_dwordx4 v164, s[92:93]
	s_barrier
; #define PG8_STAGE(bufoff, gbase, voff) do { _Pragma("unroll") for (int _i = 0; _i < 2; ++_i) \
;         __builtin_amdgcn_global_load_lds((const unsigned*)((const char*)(gbase) + (voff)[_i]), (LAS unsigned*)(lds + (bufoff) + ldsw + _i * 8192), 16, 0, 0); } while (0)
; #define PG8_LDA(dst, b, h) do { _Pragma("unroll") for (int m = 0; m < 4; ++m) _Pragma("unroll") for (int k = 0; k < 2; ++k) dst[m][k] = *(const LAS bf16x8*)(lds + PG8_SA(b, h) + aoff + m * 2048 + k * 1024); } while (0)
; #define PG8_MMA(ai, bj, At, Bt) do { __builtin_amdgcn_s_setprio(1); _Pragma("unroll") for (int m = 0; m < 4; ++m) _Pragma("unroll") for (int n = 0; n < 2; ++n) _Pragma("unroll") for (int k = 0; k < 2; ++k) \
;         acc[ai][bj][m][n] = __builtin_amdgcn_mfma_f32_16x16x32_bf16(Bt[n][k], At[m][k], acc[ai][bj][m][n], 0, 0, 0); __builtin_amdgcn_s_setprio(0); } while (0)
; #define PG8_WAIT_V(n) asm volatile("s_waitcnt vmcnt(" #n ")" ::: "memory")
; #define PG8_WAIT_L(n) asm volatile("s_waitcnt lgkmcnt(" #n ")" ::: "memory")
; #define PG8_BAR __builtin_amdgcn_s_barrier()
; #define PG8_SCHED __builtin_amdgcn_sched_barrier(0)
; template <class Epi, class Ptrs>
; __device__ __forceinline__ void gemm_phase(LAS unsigned char* lds, const int K, const StaticOrder& S, const Ptrs& P, const Epi& E) {
;     ...
;             PG8_BAR; PG8_WAIT_L(0); PG8_MMA(0, 1, At, B1); PG8_BAR;
;             PG8_LDA(At, 1, 1); PG8_STAGE(PG8_SA(1, 0), a3, voffA);
;             PG8_BAR; PG8_WAIT_L(0); PG8_MMA(1, 0, At, B0); PG8_BAR; PG8_SCHED;
;             PG8_STAGE(PG8_SB(1, 1), b3 + hstep, voffB);
;             PG8_WAIT_V(6); PG8_BAR; PG8_MMA(1, 1, At, B1); PG8_BAR;
;     __device__ __forceinline__ void operator()(const f32x4 (&acc)[2][2][4][2], const Unit& u, int ui, int wr, int wc, int fr, int fq) const {
;         const int rl0 = wr * 64 + fr, col0 = u.pn * 256 + wc * 32 + 8 * fq;
;         u32x4 xv[2][4][2];
; #pragma unroll
;         for (int ai = 0; ai < 2; ++ai)
; #pragma unroll
;             for (int m = 0; m < 4; ++m)
; #pragma unroll
;                 for (int bj = 0; bj < 2; ++bj) xv[ai][m][bj] = *(const u32x4*)(xb + (size_t)(u.pm * 256 + rl0 + ai * 128 + m * 16) * DM + col0 + bj * 128);
	s_waitcnt lgkmcnt(0)
	s_setprio 1
	s_waitcnt lgkmcnt(0)
	v_mfma_f32_16x16x32_bf16 v[60:63], v[128:131], v[144:147], v[60:63]
	v_mfma_f32_16x16x32_bf16 v[60:63], v[132:135], v[148:151], v[60:63]
	v_mfma_f32_16x16x32_bf16 v[56:59], v[140:143], v[148:151], v[56:59]
	v_mfma_f32_16x16x32_bf16 v[56:59], v[136:139], v[144:147], v[56:59]
	v_mfma_f32_16x16x32_bf16 v[40:43], v[136:139], v[152:155], v[40:43]
	v_mfma_f32_16x16x32_bf16 v[40:43], v[140:143], v[156:159], v[40:43]
	v_mfma_f32_16x16x32_bf16 v[48:51], v[132:135], v[156:159], v[48:51]
	v_mfma_f32_16x16x32_bf16 v[48:51], v[128:131], v[152:155], v[48:51]
	v_mfma_f32_16x16x32_bf16 v[32:35], v[128:131], v[176:179], v[32:35]
	v_mfma_f32_16x16x32_bf16 v[32:35], v[132:135], v[180:183], v[32:35]
	v_mfma_f32_16x16x32_bf16 v[24:27], v[140:143], v[180:183], v[24:27]
	v_mfma_f32_16x16x32_bf16 v[24:27], v[136:139], v[176:179], v[24:27]
	v_mfma_f32_16x16x32_bf16 v[8:11], v[136:139], v[196:199], v[8:11]
	v_mfma_f32_16x16x32_bf16 v[8:11], v[140:143], v[200:203], v[8:11]
	v_mfma_f32_16x16x32_bf16 v[16:19], v[132:135], v[200:203], v[16:19]
	v_mfma_f32_16x16x32_bf16 v[16:19], v[128:131], v[196:199], v[16:19]
	s_setprio 0
	s_barrier
	s_add_u32 s22, s22, 0x100080
	s_addc_u32 s23, s23, 0
	s_add_i32 s24, s24, s34
	s_mov_b32 m0, s24
	s_nop 0
	global_load_lds_dwordx4 v162, s[22:23]
	s_add_i32 m0, s24, 0x2000
	s_nop 0
	global_load_lds_dwordx4 v166, s[22:23]
	s_waitcnt vmcnt(6)
	s_barrier
	s_setprio 1
	v_mfma_f32_16x16x32_bf16 v[52:55], v[204:207], v[144:147], v[52:55]
	v_mfma_f32_16x16x32_bf16 v[52:55], v[208:211], v[148:151], v[52:55]
	v_mfma_f32_16x16x32_bf16 v[44:47], v[216:219], v[148:151], v[44:47]
	v_mfma_f32_16x16x32_bf16 v[44:47], v[212:215], v[144:147], v[44:47]
	v_mfma_f32_16x16x32_bf16 v[28:31], v[212:215], v[152:155], v[28:31]
	v_mfma_f32_16x16x32_bf16 v[28:31], v[216:219], v[156:159], v[28:31]
	v_mfma_f32_16x16x32_bf16 v[36:39], v[208:211], v[156:159], v[36:39]
	v_mfma_f32_16x16x32_bf16 v[36:39], v[204:207], v[152:155], v[36:39]
	v_mfma_f32_16x16x32_bf16 v[20:23], v[204:207], v[176:179], v[20:23]
	v_mfma_f32_16x16x32_bf16 v[20:23], v[208:211], v[180:183], v[20:23]
	v_mfma_f32_16x16x32_bf16 v[12:15], v[216:219], v[180:183], v[12:15]
	v_mfma_f32_16x16x32_bf16 v[12:15], v[212:215], v[176:179], v[12:15]
	v_mfma_f32_16x16x32_bf16 v[0:3], v[212:215], v[196:199], v[0:3]
	v_mfma_f32_16x16x32_bf16 v[0:3], v[216:219], v[200:203], v[0:3]
	v_mfma_f32_16x16x32_bf16 v[4:7], v[208:211], v[200:203], v[4:7]
	v_mfma_f32_16x16x32_bf16 v[4:7], v[204:207], v[196:199], v[4:7]
	s_setprio 0
	s_add_i32 s46, s46, 2
	s_add_u32 s20, s20, 0x100
	s_addc_u32 s21, s21, 0
	s_add_u32 s11, s11, 0x100
	s_addc_u32 s13, s13, 0
	s_cmp_gt_u32 s46, 61
	s_barrier
	s_cbranch_scc0 .LBB0_522
	s_nop 0
	s_nop 0
	s_nop 0
	s_nop 0
	s_nop 0
	s_nop 0
	s_nop 0
	s_nop 0
	s_nop 0
	s_nop 0
	s_nop 0
	s_nop 0
	s_nop 0
	s_nop 0
	s_nop 0
	s_nop 0
	s_nop 0
	s_nop 0
	s_nop 0
	s_nop 0
	s_nop 0
	s_nop 0
	s_nop 0
	s_nop 0
	s_nop 0
	s_nop 0
	s_nop 0
	s_nop 0
	s_lshl_b32 s11, s18, 8
	v_lshl_or_b32 v128, s16, 8, v191
	v_add_u32_e32 v130, s11, v186
	v_ashrrev_i32_e32 v129, 31, v128
	v_ashrrev_i32_e32 v131, 31, v130
	v_lshl_add_u64 v[132:133], v[128:129], 1, s[6:7]
	v_lshlrev_b64 v[134:135], 11, v[130:131]
	v_lshl_add_u64 v[134:135], v[132:133], 0, v[134:135]
	global_load_dwordx4 v[198:201], v[134:135], off
	global_load_dwordx4 v[202:205], v[134:135], off offset:256
	v_or_b32_e32 v134, 16, v130
	v_ashrrev_i32_e32 v135, 31, v134
	v_lshlrev_b64 v[134:135], 11, v[134:135]
	v_lshl_add_u64 v[134:135], v[132:133], 0, v[134:135]
	global_load_dwordx4 v[206:209], v[134:135], off
	global_load_dwordx4 v[210:213], v[134:135], off offset:256
	v_or_b32_e32 v136, 32, v130
	v_ashrrev_i32_e32 v137, 31, v136
	v_or_b32_e32 v138, 48, v130
	v_add_u32_e32 v184, 0x80, v130
	v_add_u32_e32 v182, 0x90, v130
	v_add_u32_e32 v180, 0xa0, v130
	v_add_u32_e32 v178, 0xb0, v130
	v_lshlrev_b64 v[176:177], 2, v[128:129]
	v_lshlrev_b64 v[128:129], 12, v[130:131]
	v_lshlrev_b64 v[130:131], 11, v[136:137]
	v_lshl_add_u64 v[130:131], v[132:133], 0, v[130:131]
	global_load_dwordx4 v[214:217], v[130:131], off
	v_ashrrev_i32_e32 v139, 31, v138
	v_ashrrev_i32_e32 v185, 31, v184
	v_ashrrev_i32_e32 v183, 31, v182
	v_ashrrev_i32_e32 v181, 31, v180
	v_ashrrev_i32_e32 v179, 31, v178
	v_lshlrev_b64 v[134:135], 11, v[138:139]
	v_lshlrev_b64 v[136:137], 11, v[184:185]
	v_lshlrev_b64 v[138:139], 11, v[182:183]
	v_lshl_add_u32 v196, s45, 10, v192
	v_lshlrev_b64 v[140:141], 11, v[180:181]
	v_lshlrev_b64 v[142:143], 11, v[178:179]
	v_lshl_add_u64 v[128:129], s[26:27], 0, v[128:129]
	v_lshl_add_u64 v[134:135], v[132:133], 0, v[134:135]
	v_lshl_add_u64 v[136:137], v[132:133], 0, v[136:137]
	v_lshl_add_u64 v[138:139], v[132:133], 0, v[138:139]
	ds_read2_b32 v[230:231], v196 offset1:16
	v_lshl_add_u64 v[234:235], v[132:133], 0, v[140:141]
	v_lshl_add_u64 v[236:237], v[132:133], 0, v[142:143]
	v_lshl_add_u64 v[238:239], v[128:129], 0, v[176:177]
	global_load_dwordx4 v[218:221], v[130:131], off offset:256
	global_load_dwordx4 v[222:225], v[134:135], off
	global_load_dwordx4 v[226:229], v[134:135], off offset:256
	global_load_dwordx4 v[156:159], v[136:137], off
	global_load_dwordx4 v[152:155], v[136:137], off offset:256
	global_load_dwordx4 v[148:151], v[138:139], off
	global_load_dwordx4 v[144:147], v[138:139], off offset:256
	global_load_dwordx4 v[140:143], v[234:235], off
	s_nop 0
	global_load_dwordx4 v[136:139], v[234:235], off offset:256
	global_load_dwordx4 v[132:135], v[236:237], off
	global_load_dwordx4 v[128:131], v[236:237], off offset:256
	v_add_u32_e32 v232, s11, v188
	v_ashrrev_i32_e32 v233, 31, v232
	s_and_b64 vcc, exec, s[0:1]
	s_mov_b32 s16, s10
	s_mov_b32 s18, s12
	s_mov_b64 s[20:21], s[4:5]
	s_mov_b64 s[22:23], s[14:15]
	s_mov_b32 s45, s44
	s_waitcnt vmcnt(0)
; __device__ __forceinline__ float bf_lo(unsigned w) { return __uint_as_float(w << 16); }
; __device__ __forceinline__ float bf_hi(unsigned w) { return __uint_as_float(w & 0xffff0000u); }
;     __device__ __forceinline__ void operator()(const f32x4 (&acc)[2][2][4][2], const Unit& u, int ui, int wr, int wc, int fr, int fq) const {
;     ...
;             for (int m = 0; m < 4; ++m) { const int rl = rl0 + ai * 128 + m * 16; float* rowp = out + (size_t)(u.pm * 256 + rl) * DM + col0;
;                 const float r2 = tab[ui * 256 + rl];
; #pragma unroll
;                 for (int bj = 0; bj < 2; ++bj) { const u32x4 x = xv[ai][m][bj];
;                     const f32x4 x0 = {bf_lo(x.x), bf_hi(x.x), bf_lo(x.y), bf_hi(x.y)}, x1 = {bf_lo(x.z), bf_hi(x.z), bf_lo(x.w), bf_hi(x.w)};
;                     *(f32x4*)(rowp + bj * 128) = acc[ai][bj][m][0] * r2 + x0; *(f32x4*)(rowp + bj * 128 + 4) = acc[ai][bj][m][1] * r2 + x1; } }
	v_lshlrev_b32_e32 v234, 16, v198
	v_and_b32_e32 v235, 0xffff0000, v198
	v_lshlrev_b32_e32 v198, 16, v199
	v_and_b32_e32 v199, 0xffff0000, v199
	v_lshlrev_b32_e32 v242, 16, v204
	v_and_b32_e32 v243, 0xffff0000, v204
	v_lshlrev_b32_e32 v236, 16, v200
	v_and_b32_e32 v237, 0xffff0000, v200
	v_lshlrev_b32_e32 v200, 16, v201
	v_and_b32_e32 v201, 0xffff0000, v201
	v_lshlrev_b32_e32 v240, 16, v202
	v_and_b32_e32 v241, 0xffff0000, v202
	v_lshlrev_b32_e32 v202, 16, v203
	v_and_b32_e32 v203, 0xffff0000, v203
	v_lshlrev_b32_e32 v204, 16, v205
	v_and_b32_e32 v205, 0xffff0000, v205
	s_waitcnt lgkmcnt(0)
	v_pk_fma_f32 v[126:127], v[126:127], v[230:231], v[198:199] op_sel_hi:[1,0,1]
	v_pk_fma_f32 v[124:125], v[124:125], v[230:231], v[234:235] op_sel_hi:[1,0,1]
	v_pk_fma_f32 v[108:109], v[108:109], v[230:231], v[242:243] op_sel_hi:[1,0,1]
	v_pk_fma_f32 v[122:123], v[122:123], v[230:231], v[200:201] op_sel_hi:[1,0,1]
	v_pk_fma_f32 v[120:121], v[120:121], v[230:231], v[236:237] op_sel_hi:[1,0,1]
	v_pk_fma_f32 v[118:119], v[118:119], v[230:231], v[202:203] op_sel_hi:[1,0,1]
	v_pk_fma_f32 v[116:117], v[116:117], v[230:231], v[240:241] op_sel_hi:[1,0,1]
	v_pk_fma_f32 v[110:111], v[110:111], v[230:231], v[204:205] op_sel_hi:[1,0,1]
	global_store_dwordx4 v[238:239], v[124:127], off
	global_store_dwordx4 v[238:239], v[120:123], off offset:16
	global_store_dwordx4 v[238:239], v[116:119], off offset:512
	global_store_dwordx4 v[238:239], v[108:111], off offset:528
	v_mov_b32_e32 v122, v231
	v_lshlrev_b32_e32 v118, 16, v208
	v_lshlrev_b64 v[108:109], 12, v[232:233]
	v_lshl_add_u64 v[108:109], s[26:27], 0, v[108:109]
	v_lshl_add_u64 v[116:117], v[108:109], 0, v[176:177]
	v_lshlrev_b32_e32 v108, 16, v206
	v_and_b32_e32 v109, 0xffff0000, v206
	v_lshlrev_b32_e32 v110, 16, v207
	v_and_b32_e32 v111, 0xffff0000, v207
	v_pk_fma_f32 v[110:111], v[114:115], v[122:123], v[110:111] op_sel_hi:[1,0,1]
	v_pk_fma_f32 v[108:109], v[112:113], v[122:123], v[108:109] op_sel_hi:[1,0,1]
	global_store_dwordx4 v[116:117], v[108:111], off
	v_and_b32_e32 v119, 0xffff0000, v208
	v_lshlrev_b32_e32 v120, 16, v209
	v_lshlrev_b32_e32 v108, 16, v212
	v_and_b32_e32 v109, 0xffff0000, v212
	v_lshlrev_b32_e32 v110, 16, v213
	v_and_b32_e32 v111, 0xffff0000, v213
	v_pk_fma_f32 v[98:99], v[98:99], v[122:123], v[110:111] op_sel_hi:[1,0,1]
	v_pk_fma_f32 v[96:97], v[96:97], v[122:123], v[108:109] op_sel_hi:[1,0,1]
	v_and_b32_e32 v121, 0xffff0000, v209
	global_store_dwordx4 v[116:117], v[96:99], off offset:528
	ds_read2_b32 v[98:99], v196 offset0:32 offset1:48
	v_pk_fma_f32 v[106:107], v[106:107], v[122:123], v[120:121] op_sel_hi:[1,0,1]
	v_pk_fma_f32 v[104:105], v[104:105], v[122:123], v[118:119] op_sel_hi:[1,0,1]
	v_add_u32_e32 v96, s11, v189
	global_store_dwordx4 v[116:117], v[104:107], off offset:16
	v_ashrrev_i32_e32 v97, 31, v96
	v_lshlrev_b64 v[96:97], 12, v[96:97]
	v_lshlrev_b32_e32 v104, 16, v210
	v_and_b32_e32 v105, 0xffff0000, v210
	v_lshlrev_b32_e32 v106, 16, v211
	v_and_b32_e32 v107, 0xffff0000, v211
	v_pk_fma_f32 v[102:103], v[102:103], v[122:123], v[106:107] op_sel_hi:[1,0,1]
	v_pk_fma_f32 v[100:101], v[100:101], v[122:123], v[104:105] op_sel_hi:[1,0,1]
	global_store_dwordx4 v[116:117], v[100:103], off offset:512
	v_lshl_add_u64 v[96:97], s[26:27], 0, v[96:97]
	v_lshl_add_u64 v[96:97], v[96:97], 0, v[176:177]
	v_lshlrev_b32_e32 v100, 16, v214
	v_and_b32_e32 v101, 0xffff0000, v214
	v_lshlrev_b32_e32 v102, 16, v215
	v_and_b32_e32 v103, 0xffff0000, v215
	s_waitcnt lgkmcnt(0)
	v_pk_fma_f32 v[94:95], v[94:95], v[98:99], v[102:103] op_sel_hi:[1,0,1]
	v_pk_fma_f32 v[92:93], v[92:93], v[98:99], v[100:101] op_sel_hi:[1,0,1]
	global_store_dwordx4 v[96:97], v[92:95], off
	v_lshlrev_b32_e32 v104, 16, v216
	v_and_b32_e32 v105, 0xffff0000, v216
	v_lshlrev_b32_e32 v92, 16, v220
	v_and_b32_e32 v93, 0xffff0000, v220
	v_lshlrev_b32_e32 v94, 16, v221
	v_and_b32_e32 v95, 0xffff0000, v221
	v_lshlrev_b32_e32 v106, 16, v217
	v_and_b32_e32 v107, 0xffff0000, v217
	v_pk_fma_f32 v[82:83], v[82:83], v[98:99], v[94:95] op_sel_hi:[1,0,1]
	v_pk_fma_f32 v[80:81], v[80:81], v[98:99], v[92:93] op_sel_hi:[1,0,1]
	v_pk_fma_f32 v[90:91], v[90:91], v[98:99], v[106:107] op_sel_hi:[1,0,1]
	v_pk_fma_f32 v[88:89], v[88:89], v[98:99], v[104:105] op_sel_hi:[1,0,1]
	global_store_dwordx4 v[96:97], v[80:83], off offset:528
	global_store_dwordx4 v[96:97], v[88:91], off offset:16
	s_nop 0
	v_add_u32_e32 v80, s11, v190
	v_lshlrev_b32_e32 v88, 16, v218
	v_and_b32_e32 v89, 0xffff0000, v218
	v_lshlrev_b32_e32 v90, 16, v219
	v_and_b32_e32 v91, 0xffff0000, v219
	v_ashrrev_i32_e32 v81, 31, v80
	v_pk_fma_f32 v[86:87], v[86:87], v[98:99], v[90:91] op_sel_hi:[1,0,1]
	v_pk_fma_f32 v[84:85], v[84:85], v[98:99], v[88:89] op_sel_hi:[1,0,1]
	v_lshlrev_b64 v[80:81], 12, v[80:81]
	global_store_dwordx4 v[96:97], v[84:87], off offset:512
	v_lshl_add_u64 v[80:81], s[26:27], 0, v[80:81]
	v_lshlrev_b32_e32 v82, 16, v222
	v_and_b32_e32 v83, 0xffff0000, v222
	v_lshlrev_b32_e32 v84, 16, v223
	v_and_b32_e32 v85, 0xffff0000, v223
	v_mov_b32_e32 v90, v99
	v_lshl_add_u64 v[80:81], v[80:81], 0, v[176:177]
	v_pk_fma_f32 v[78:79], v[78:79], v[90:91], v[84:85] op_sel_hi:[1,0,1]
	v_pk_fma_f32 v[76:77], v[76:77], v[90:91], v[82:83] op_sel_hi:[1,0,1]
	global_store_dwordx4 v[80:81], v[76:79], off
	v_lshlrev_b32_e32 v86, 16, v224
	v_and_b32_e32 v87, 0xffff0000, v224
	v_lshlrev_b32_e32 v76, 16, v228
	v_and_b32_e32 v77, 0xffff0000, v228
	v_lshlrev_b32_e32 v78, 16, v229
	v_and_b32_e32 v79, 0xffff0000, v229
	v_pk_fma_f32 v[66:67], v[66:67], v[90:91], v[78:79] op_sel_hi:[1,0,1]
	v_pk_fma_f32 v[64:65], v[64:65], v[90:91], v[76:77] op_sel_hi:[1,0,1]
	v_lshlrev_b32_e32 v88, 16, v225
	v_and_b32_e32 v89, 0xffff0000, v225
	global_store_dwordx4 v[80:81], v[64:67], off offset:528
	ds_read2_b32 v[66:67], v196 offset0:128 offset1:144
	v_pk_fma_f32 v[74:75], v[74:75], v[90:91], v[88:89] op_sel_hi:[1,0,1]
	v_pk_fma_f32 v[72:73], v[72:73], v[90:91], v[86:87] op_sel_hi:[1,0,1]
	global_store_dwordx4 v[80:81], v[72:75], off offset:16
	v_lshlrev_b64 v[64:65], 12, v[184:185]
	v_lshl_add_u64 v[64:65], s[26:27], 0, v[64:65]
	v_lshlrev_b32_e32 v72, 16, v226
	v_and_b32_e32 v73, 0xffff0000, v226
	v_lshlrev_b32_e32 v74, 16, v227
	v_and_b32_e32 v75, 0xffff0000, v227
	v_pk_fma_f32 v[70:71], v[70:71], v[90:91], v[74:75] op_sel_hi:[1,0,1]
	v_pk_fma_f32 v[68:69], v[68:69], v[90:91], v[72:73] op_sel_hi:[1,0,1]
	global_store_dwordx4 v[80:81], v[68:71], off offset:512
	v_lshl_add_u64 v[64:65], v[64:65], 0, v[176:177]
	v_lshlrev_b32_e32 v72, 16, v158
	v_lshlrev_b32_e32 v68, 16, v156
	v_and_b32_e32 v69, 0xffff0000, v156
	v_lshlrev_b32_e32 v70, 16, v157
	v_and_b32_e32 v71, 0xffff0000, v157
	v_and_b32_e32 v73, 0xffff0000, v158
	v_lshlrev_b32_e32 v74, 16, v159
	v_and_b32_e32 v75, 0xffff0000, v159
	s_waitcnt lgkmcnt(0)
; __device__ __forceinline__ float bf_lo(unsigned w) { return __uint_as_float(w << 16); }
; __device__ __forceinline__ float bf_hi(unsigned w) { return __uint_as_float(w & 0xffff0000u); }
; #define PG8_WAIT_V(n) asm volatile("s_waitcnt vmcnt(" #n ")" ::: "memory")
; #define PG8_BAR __builtin_amdgcn_s_barrier()
; template <class Epi, class Ptrs>
; __device__ __forceinline__ void gemm_phase(LAS unsigned char* lds, const int K, const StaticOrder& S, const Ptrs& P, const Epi& E) {
;     ...
;         cur = nxt; cA = nA; cB = nB; ++ui;
;     }
;     PG8_WAIT_V(0);
;     if (wr == 0) PG8_BAR;
;     PG8_BAR;
;     __device__ __forceinline__ void operator()(const f32x4 (&acc)[2][2][4][2], const Unit& u, int ui, int wr, int wc, int fr, int fq) const {
;     ...
;             for (int m = 0; m < 4; ++m) { const int rl = rl0 + ai * 128 + m * 16; float* rowp = out + (size_t)(u.pm * 256 + rl) * DM + col0;
;                 const float r2 = tab[ui * 256 + rl];
; #pragma unroll
;                 for (int bj = 0; bj < 2; ++bj) { const u32x4 x = xv[ai][m][bj];
;                     const f32x4 x0 = {bf_lo(x.x), bf_hi(x.x), bf_lo(x.y), bf_hi(x.y)}, x1 = {bf_lo(x.z), bf_hi(x.z), bf_lo(x.w), bf_hi(x.w)};
;                     *(f32x4*)(rowp + bj * 128) = acc[ai][bj][m][0] * r2 + x0; *(f32x4*)(rowp + bj * 128 + 4) = acc[ai][bj][m][1] * r2 + x1; } }
	v_pk_fma_f32 v[62:63], v[62:63], v[66:67], v[70:71] op_sel_hi:[1,0,1]
	v_pk_fma_f32 v[60:61], v[60:61], v[66:67], v[68:69] op_sel_hi:[1,0,1]
	global_store_dwordx4 v[64:65], v[60:63], off
	v_pk_fma_f32 v[58:59], v[58:59], v[66:67], v[74:75] op_sel_hi:[1,0,1]
	v_pk_fma_f32 v[56:57], v[56:57], v[66:67], v[72:73] op_sel_hi:[1,0,1]
	v_lshlrev_b32_e32 v60, 16, v154
	v_and_b32_e32 v61, 0xffff0000, v154
	v_lshlrev_b32_e32 v62, 16, v155
	v_and_b32_e32 v63, 0xffff0000, v155
	global_store_dwordx4 v[64:65], v[56:59], off offset:16
	v_pk_fma_f32 v[46:47], v[46:47], v[66:67], v[62:63] op_sel_hi:[1,0,1]
	v_pk_fma_f32 v[44:45], v[44:45], v[66:67], v[60:61] op_sel_hi:[1,0,1]
	v_lshlrev_b32_e32 v56, 16, v152
	v_and_b32_e32 v57, 0xffff0000, v152
	v_lshlrev_b32_e32 v58, 16, v153
	v_and_b32_e32 v59, 0xffff0000, v153
	v_pk_fma_f32 v[54:55], v[54:55], v[66:67], v[58:59] op_sel_hi:[1,0,1]
	v_pk_fma_f32 v[52:53], v[52:53], v[66:67], v[56:57] op_sel_hi:[1,0,1]
	global_store_dwordx4 v[64:65], v[44:47], off offset:528
	global_store_dwordx4 v[64:65], v[52:55], off offset:512
	v_lshlrev_b32_e32 v56, 16, v151
	v_lshlrev_b64 v[44:45], 12, v[182:183]
	v_lshl_add_u64 v[44:45], s[26:27], 0, v[44:45]
	v_lshlrev_b32_e32 v54, 16, v150
	v_and_b32_e32 v55, 0xffff0000, v150
	v_and_b32_e32 v57, 0xffff0000, v151
	v_mov_b32_e32 v58, v67
	v_lshl_add_u64 v[52:53], v[44:45], 0, v[176:177]
	v_pk_fma_f32 v[42:43], v[42:43], v[58:59], v[56:57] op_sel_hi:[1,0,1]
	v_pk_fma_f32 v[40:41], v[40:41], v[58:59], v[54:55] op_sel_hi:[1,0,1]
	v_lshlrev_b32_e32 v44, 16, v148
	v_and_b32_e32 v45, 0xffff0000, v148
	v_lshlrev_b32_e32 v46, 16, v149
	v_and_b32_e32 v47, 0xffff0000, v149
	global_store_dwordx4 v[52:53], v[40:43], off offset:16
	v_pk_fma_f32 v[46:47], v[50:51], v[58:59], v[46:47] op_sel_hi:[1,0,1]
	v_pk_fma_f32 v[44:45], v[48:49], v[58:59], v[44:45] op_sel_hi:[1,0,1]
	v_lshlrev_b32_e32 v40, 16, v144
	v_and_b32_e32 v41, 0xffff0000, v144
	v_lshlrev_b32_e32 v42, 16, v145
	v_and_b32_e32 v43, 0xffff0000, v145
	v_pk_fma_f32 v[38:39], v[38:39], v[58:59], v[42:43] op_sel_hi:[1,0,1]
	v_pk_fma_f32 v[36:37], v[36:37], v[58:59], v[40:41] op_sel_hi:[1,0,1]
	global_store_dwordx4 v[52:53], v[44:47], off
	global_store_dwordx4 v[52:53], v[36:39], off offset:512
	ds_read2_b32 v[38:39], v196 offset0:160 offset1:176
	v_lshlrev_b32_e32 v44, 16, v146
	v_and_b32_e32 v45, 0xffff0000, v146
	v_lshlrev_b32_e32 v46, 16, v147
	v_and_b32_e32 v47, 0xffff0000, v147
	v_pk_fma_f32 v[30:31], v[30:31], v[58:59], v[46:47] op_sel_hi:[1,0,1]
	v_pk_fma_f32 v[28:29], v[28:29], v[58:59], v[44:45] op_sel_hi:[1,0,1]
	global_store_dwordx4 v[52:53], v[28:31], off offset:528
	v_lshlrev_b32_e32 v40, 16, v142
	v_and_b32_e32 v41, 0xffff0000, v142
	v_lshlrev_b64 v[28:29], 12, v[180:181]
	v_lshl_add_u64 v[28:29], s[26:27], 0, v[28:29]
	v_lshl_add_u64 v[36:37], v[28:29], 0, v[176:177]
	v_lshlrev_b32_e32 v28, 16, v140
	v_and_b32_e32 v29, 0xffff0000, v140
	v_lshlrev_b32_e32 v30, 16, v141
	v_and_b32_e32 v31, 0xffff0000, v141
	s_waitcnt lgkmcnt(0)
	v_pk_fma_f32 v[30:31], v[34:35], v[38:39], v[30:31] op_sel_hi:[1,0,1]
	v_pk_fma_f32 v[28:29], v[32:33], v[38:39], v[28:29] op_sel_hi:[1,0,1]
	v_lshlrev_b32_e32 v42, 16, v143
	v_and_b32_e32 v43, 0xffff0000, v143
	global_store_dwordx4 v[36:37], v[28:31], off
	v_pk_fma_f32 v[26:27], v[26:27], v[38:39], v[42:43] op_sel_hi:[1,0,1]
	v_pk_fma_f32 v[24:25], v[24:25], v[38:39], v[40:41] op_sel_hi:[1,0,1]
	v_lshlrev_b32_e32 v28, 16, v138
	v_and_b32_e32 v29, 0xffff0000, v138
	v_lshlrev_b32_e32 v30, 16, v139
	v_and_b32_e32 v31, 0xffff0000, v139
	v_pk_fma_f32 v[14:15], v[14:15], v[38:39], v[30:31] op_sel_hi:[1,0,1]
	v_pk_fma_f32 v[12:13], v[12:13], v[38:39], v[28:29] op_sel_hi:[1,0,1]
	global_store_dwordx4 v[36:37], v[24:27], off offset:16
	global_store_dwordx4 v[36:37], v[12:15], off offset:528
	s_nop 0
	v_lshlrev_b32_e32 v24, 16, v136
	v_and_b32_e32 v25, 0xffff0000, v136
	v_lshlrev_b32_e32 v26, 16, v137
	v_and_b32_e32 v27, 0xffff0000, v137
	v_lshlrev_b64 v[12:13], 12, v[178:179]
	v_pk_fma_f32 v[22:23], v[22:23], v[38:39], v[26:27] op_sel_hi:[1,0,1]
	v_pk_fma_f32 v[20:21], v[20:21], v[38:39], v[24:25] op_sel_hi:[1,0,1]
	v_lshl_add_u64 v[12:13], s[26:27], 0, v[12:13]
	global_store_dwordx4 v[36:37], v[20:23], off offset:512
	v_lshlrev_b32_e32 v14, 16, v133
	v_and_b32_e32 v15, 0xffff0000, v133
	v_lshl_add_u64 v[20:21], v[12:13], 0, v[176:177]
	v_lshlrev_b32_e32 v12, 16, v132
	v_and_b32_e32 v13, 0xffff0000, v132
	v_lshlrev_b32_e32 v22, 16, v134
	v_and_b32_e32 v23, 0xffff0000, v134
	v_lshlrev_b32_e32 v24, 16, v135
	v_and_b32_e32 v25, 0xffff0000, v135
	v_mov_b32_e32 v26, v39
	v_pk_fma_f32 v[14:15], v[18:19], v[26:27], v[14:15] op_sel_hi:[1,0,1]
	v_pk_fma_f32 v[12:13], v[16:17], v[26:27], v[12:13] op_sel_hi:[1,0,1]
	v_pk_fma_f32 v[10:11], v[10:11], v[26:27], v[24:25] op_sel_hi:[1,0,1]
	v_pk_fma_f32 v[8:9], v[8:9], v[26:27], v[22:23] op_sel_hi:[1,0,1]
	global_store_dwordx4 v[20:21], v[12:15], off
	global_store_dwordx4 v[20:21], v[8:11], off offset:16
	s_nop 0
	v_lshlrev_b32_e32 v12, 16, v130
	v_lshlrev_b32_e32 v8, 16, v128
	v_and_b32_e32 v9, 0xffff0000, v128
	v_lshlrev_b32_e32 v10, 16, v129
	v_and_b32_e32 v11, 0xffff0000, v129
	v_and_b32_e32 v13, 0xffff0000, v130
	v_lshlrev_b32_e32 v14, 16, v131
	v_and_b32_e32 v15, 0xffff0000, v131
	v_pk_fma_f32 v[6:7], v[6:7], v[26:27], v[10:11] op_sel_hi:[1,0,1]
	v_pk_fma_f32 v[4:5], v[4:5], v[26:27], v[8:9] op_sel_hi:[1,0,1]
	v_pk_fma_f32 v[2:3], v[2:3], v[26:27], v[14:15] op_sel_hi:[1,0,1]
	v_pk_fma_f32 v[0:1], v[0:1], v[26:27], v[12:13] op_sel_hi:[1,0,1]
	global_store_dwordx4 v[20:21], v[4:7], off offset:512
	global_store_dwordx4 v[20:21], v[0:3], off offset:528
	s_cbranch_vccz .LBB0_517
	s_waitcnt vmcnt(0)
	s_cmpk_gt_u32 s33, 0xff
	s_cbranch_scc1 .LBB0_526
	s_barrier
